# GEMM K loops: remaining 64-bit VGPR DMA addresses as scalar base pairs, on top of the cleaned loops
# speedup vs baseline: 1.0011x; 1.0011x over previous
.LBB0_272:
	ds_read_b128 v[146:149], v153
	ds_read_b128 v[156:159], v153 offset:1024
	ds_read_b128 v[160:163], v153 offset:2048
	ds_read_b128 v[164:167], v153 offset:3072
	ds_read_b128 v[168:171], v154
	ds_read_b128 v[172:175], v154 offset:1024
	ds_read_b128 v[176:179], v154 offset:2048
	ds_read_b128 v[180:183], v154 offset:3072
	s_add_u32 s62, s60, 0xfffc0080
	s_addc_u32 s63, s61, -1
	s_cmp_eq_u32 s86, 12
	s_cselect_b32 s65, s37, s63
	s_cselect_b32 s64, s43, s62
	s_cselect_b32 s63, s35, s85
	s_cselect_b32 s62, s55, s84
	s_add_i32 m0, s69, 0xc000
	ds_read_b128 v[184:187], v155
	ds_read_b128 v[192:195], v155 offset:1024
	ds_read_b128 v[196:199], v155 offset:2048
	ds_read_b128 v[200:203], v155 offset:3072
	ds_read_b128 v[204:207], v155 offset:4096
	ds_read_b128 v[208:211], v155 offset:5120
	ds_read_b128 v[212:215], v155 offset:6144
	ds_read_b128 v[216:219], v155 offset:7168
	global_load_lds_dwordx4 v138, s[60:61]
	v_lshl_add_u64 v[188:189], s[60:61], 0, v[140:141]
	s_add_i32 m0, s69, 0xe000
	s_nop 0
	global_load_lds_dwordx4 v[188:189], off
	s_waitcnt vmcnt(8)
	s_waitcnt lgkmcnt(0)
	s_barrier
	v_mfma_f32_16x16x32_bf16 v[124:127], v[146:149], v[184:187], v[124:127]
	v_mfma_f32_16x16x32_bf16 v[120:123], v[160:163], v[184:187], v[120:123]
	v_mfma_f32_16x16x32_bf16 v[116:119], v[146:149], v[196:199], v[116:119]
	v_mfma_f32_16x16x32_bf16 v[108:111], v[160:163], v[196:199], v[108:111]
	v_mfma_f32_16x16x32_bf16 v[100:103], v[146:149], v[204:207], v[100:103]
	v_mfma_f32_16x16x32_bf16 v[92:95], v[160:163], v[204:207], v[92:95]
	v_mfma_f32_16x16x32_bf16 v[84:87], v[146:149], v[212:215], v[84:87]
	v_mfma_f32_16x16x32_bf16 v[76:79], v[160:163], v[212:215], v[76:79]
	v_mfma_f32_16x16x32_bf16 v[124:127], v[156:159], v[192:195], v[124:127]
	v_mfma_f32_16x16x32_bf16 v[120:123], v[164:167], v[192:195], v[120:123]
	v_mfma_f32_16x16x32_bf16 v[116:119], v[156:159], v[200:203], v[116:119]
	v_mfma_f32_16x16x32_bf16 v[108:111], v[164:167], v[200:203], v[108:111]
	v_mfma_f32_16x16x32_bf16 v[100:103], v[156:159], v[208:211], v[100:103]
	v_mfma_f32_16x16x32_bf16 v[92:95], v[164:167], v[208:211], v[92:95]
	v_mfma_f32_16x16x32_bf16 v[84:87], v[156:159], v[216:219], v[84:87]
	v_mfma_f32_16x16x32_bf16 v[76:79], v[164:167], v[216:219], v[76:79]
	v_mfma_f32_16x16x32_bf16 v[112:115], v[168:171], v[184:187], v[112:115]
	v_mfma_f32_16x16x32_bf16 v[104:107], v[176:179], v[184:187], v[104:107]
	v_mfma_f32_16x16x32_bf16 v[96:99], v[168:171], v[196:199], v[96:99]
	v_mfma_f32_16x16x32_bf16 v[88:91], v[176:179], v[196:199], v[88:91]
	v_mfma_f32_16x16x32_bf16 v[80:83], v[168:171], v[204:207], v[80:83]
	v_mfma_f32_16x16x32_bf16 v[72:75], v[176:179], v[204:207], v[72:75]
	v_mfma_f32_16x16x32_bf16 v[68:71], v[168:171], v[212:215], v[68:71]
	v_mfma_f32_16x16x32_bf16 v[64:67], v[176:179], v[212:215], v[64:67]
	v_mfma_f32_16x16x32_bf16 v[112:115], v[172:175], v[192:195], v[112:115]
	v_mfma_f32_16x16x32_bf16 v[104:107], v[180:183], v[192:195], v[104:107]
	v_mfma_f32_16x16x32_bf16 v[96:99], v[172:175], v[200:203], v[96:99]
	v_mfma_f32_16x16x32_bf16 v[88:91], v[180:183], v[200:203], v[88:91]
	v_mfma_f32_16x16x32_bf16 v[80:83], v[172:175], v[208:211], v[80:83]
	v_mfma_f32_16x16x32_bf16 v[72:75], v[180:183], v[208:211], v[72:75]
	v_mfma_f32_16x16x32_bf16 v[68:71], v[172:175], v[216:219], v[68:71]
	v_mfma_f32_16x16x32_bf16 v[64:67], v[180:183], v[216:219], v[64:67]
	s_barrier
	s_add_i32 s87, s76, s68
	s_add_u32 s98, s62, 0x80
	s_addc_u32 s99, s63, 0
	s_mov_b32 m0, s87
	ds_read_b128 v[184:187], v155 offset:16384
	ds_read_b128 v[192:195], v155 offset:17408
	ds_read_b128 v[196:199], v155 offset:18432
	ds_read_b128 v[200:203], v155 offset:19456
	ds_read_b128 v[204:207], v155 offset:20480
	ds_read_b128 v[208:211], v155 offset:21504
	ds_read_b128 v[212:215], v155 offset:22528
	ds_read_b128 v[216:219], v155 offset:23552
	global_load_lds_dwordx4 v132, s[62:63]
	s_add_i32 m0, s87, 0x2000
	s_add_u32 s88, s62, 0x40000
	s_addc_u32 s89, s63, 0
	s_add_i32 s87, s77, s68
	global_load_lds_dwordx4 v128, s[62:63]
	s_mov_b32 m0, s87
	s_add_u32 s100, s64, 0x80
	s_addc_u32 s101, s65, 0
	global_load_lds_dwordx4 v132, s[88:89]
	s_add_i32 m0, s87, 0x2000
	s_nop 0
	global_load_lds_dwordx4 v128, s[88:89]
	s_mov_b32 m0, s69
	s_nop 0
	global_load_lds_dwordx4 v134, s[64:65]
	s_mov_b32 m0, s70
	s_nop 0
	global_load_lds_dwordx4 v130, s[64:65]
	s_waitcnt vmcnt(8)
	s_waitcnt lgkmcnt(0)
	s_barrier
	v_mfma_f32_16x16x32_bf16 v[60:63], v[146:149], v[184:187], v[60:63]
	v_mfma_f32_16x16x32_bf16 v[56:59], v[160:163], v[184:187], v[56:59]
	v_mfma_f32_16x16x32_bf16 v[52:55], v[146:149], v[196:199], v[52:55]
	v_mfma_f32_16x16x32_bf16 v[44:47], v[160:163], v[196:199], v[44:47]
	v_mfma_f32_16x16x32_bf16 v[36:39], v[146:149], v[204:207], v[36:39]
	v_mfma_f32_16x16x32_bf16 v[28:31], v[160:163], v[204:207], v[28:31]
	v_mfma_f32_16x16x32_bf16 v[20:23], v[146:149], v[212:215], v[20:23]
	v_mfma_f32_16x16x32_bf16 v[12:15], v[160:163], v[212:215], v[12:15]
	v_mfma_f32_16x16x32_bf16 v[60:63], v[156:159], v[192:195], v[60:63]
	v_mfma_f32_16x16x32_bf16 v[56:59], v[164:167], v[192:195], v[56:59]
	v_mfma_f32_16x16x32_bf16 v[52:55], v[156:159], v[200:203], v[52:55]
	v_mfma_f32_16x16x32_bf16 v[44:47], v[164:167], v[200:203], v[44:47]
	v_mfma_f32_16x16x32_bf16 v[36:39], v[156:159], v[208:211], v[36:39]
	v_mfma_f32_16x16x32_bf16 v[28:31], v[164:167], v[208:211], v[28:31]
	v_mfma_f32_16x16x32_bf16 v[20:23], v[156:159], v[216:219], v[20:23]
	v_mfma_f32_16x16x32_bf16 v[12:15], v[164:167], v[216:219], v[12:15]
	v_mfma_f32_16x16x32_bf16 v[48:51], v[168:171], v[184:187], v[48:51]
	v_mfma_f32_16x16x32_bf16 v[40:43], v[176:179], v[184:187], v[40:43]
	v_mfma_f32_16x16x32_bf16 v[32:35], v[168:171], v[196:199], v[32:35]
	v_mfma_f32_16x16x32_bf16 v[24:27], v[176:179], v[196:199], v[24:27]
	v_mfma_f32_16x16x32_bf16 v[16:19], v[168:171], v[204:207], v[16:19]
	v_mfma_f32_16x16x32_bf16 v[8:11], v[176:179], v[204:207], v[8:11]
	v_mfma_f32_16x16x32_bf16 v[4:7], v[168:171], v[212:215], v[4:7]
	v_mfma_f32_16x16x32_bf16 v[0:3], v[176:179], v[212:215], v[0:3]
	v_mfma_f32_16x16x32_bf16 v[48:51], v[172:175], v[192:195], v[48:51]
	v_mfma_f32_16x16x32_bf16 v[40:43], v[180:183], v[192:195], v[40:43]
	v_mfma_f32_16x16x32_bf16 v[32:35], v[172:175], v[200:203], v[32:35]
	v_mfma_f32_16x16x32_bf16 v[24:27], v[180:183], v[200:203], v[24:27]
	v_mfma_f32_16x16x32_bf16 v[16:19], v[172:175], v[208:211], v[16:19]
	v_mfma_f32_16x16x32_bf16 v[8:11], v[180:183], v[208:211], v[8:11]
	v_mfma_f32_16x16x32_bf16 v[4:7], v[172:175], v[216:219], v[4:7]
	v_mfma_f32_16x16x32_bf16 v[0:3], v[180:183], v[216:219], v[0:3]
	s_barrier
	s_add_i32 s87, 0, 0x18000
	s_add_i32 s88, 0, 0x1c000
	v_add_u32_e32 v164, s87, v151
	v_add_u32_e32 v180, s88, v151
	ds_read_b128 v[146:149], v164
	ds_read_b128 v[156:159], v164 offset:1024
	ds_read_b128 v[160:163], v164 offset:2048
	ds_read_b128 v[164:167], v164 offset:3072
	ds_read_b128 v[168:171], v180
	ds_read_b128 v[172:175], v180 offset:1024
	ds_read_b128 v[176:179], v180 offset:2048
	ds_read_b128 v[180:183], v180 offset:3072
	s_add_u32 s64, s64, 0x40000
	s_addc_u32 s65, s65, 0
	s_mov_b32 m0, s71
	ds_read_b128 v[184:187], v155 offset:32768
	ds_read_b128 v[192:195], v155 offset:33792
	ds_read_b128 v[196:199], v155 offset:34816
	ds_read_b128 v[200:203], v155 offset:35840
	ds_read_b128 v[204:207], v155 offset:36864
	ds_read_b128 v[208:211], v155 offset:37888
	ds_read_b128 v[212:215], v155 offset:38912
	ds_read_b128 v[216:219], v155 offset:39936
	global_load_lds_dwordx4 v134, s[64:65]
	s_mov_b32 m0, s72
	s_nop 0
	global_load_lds_dwordx4 v130, s[64:65]
	s_waitcnt vmcnt(8)
	s_waitcnt lgkmcnt(0)
	s_barrier
	v_mfma_f32_16x16x32_bf16 v[124:127], v[146:149], v[184:187], v[124:127]
	v_mfma_f32_16x16x32_bf16 v[120:123], v[160:163], v[184:187], v[120:123]
	v_mfma_f32_16x16x32_bf16 v[116:119], v[146:149], v[196:199], v[116:119]
	v_mfma_f32_16x16x32_bf16 v[108:111], v[160:163], v[196:199], v[108:111]
	v_mfma_f32_16x16x32_bf16 v[100:103], v[146:149], v[204:207], v[100:103]
	v_mfma_f32_16x16x32_bf16 v[92:95], v[160:163], v[204:207], v[92:95]
	v_mfma_f32_16x16x32_bf16 v[84:87], v[146:149], v[212:215], v[84:87]
	v_mfma_f32_16x16x32_bf16 v[76:79], v[160:163], v[212:215], v[76:79]
	v_mfma_f32_16x16x32_bf16 v[124:127], v[156:159], v[192:195], v[124:127]
	v_mfma_f32_16x16x32_bf16 v[120:123], v[164:167], v[192:195], v[120:123]
	v_mfma_f32_16x16x32_bf16 v[116:119], v[156:159], v[200:203], v[116:119]
	v_mfma_f32_16x16x32_bf16 v[108:111], v[164:167], v[200:203], v[108:111]
	v_mfma_f32_16x16x32_bf16 v[100:103], v[156:159], v[208:211], v[100:103]
	v_mfma_f32_16x16x32_bf16 v[92:95], v[164:167], v[208:211], v[92:95]
	v_mfma_f32_16x16x32_bf16 v[84:87], v[156:159], v[216:219], v[84:87]
	v_mfma_f32_16x16x32_bf16 v[76:79], v[164:167], v[216:219], v[76:79]
	v_mfma_f32_16x16x32_bf16 v[112:115], v[168:171], v[184:187], v[112:115]
	v_mfma_f32_16x16x32_bf16 v[104:107], v[176:179], v[184:187], v[104:107]
	v_mfma_f32_16x16x32_bf16 v[96:99], v[168:171], v[196:199], v[96:99]
	v_mfma_f32_16x16x32_bf16 v[88:91], v[176:179], v[196:199], v[88:91]
	v_mfma_f32_16x16x32_bf16 v[80:83], v[168:171], v[204:207], v[80:83]
	v_mfma_f32_16x16x32_bf16 v[72:75], v[176:179], v[204:207], v[72:75]
	v_mfma_f32_16x16x32_bf16 v[68:71], v[168:171], v[212:215], v[68:71]
	v_mfma_f32_16x16x32_bf16 v[64:67], v[176:179], v[212:215], v[64:67]
	v_mfma_f32_16x16x32_bf16 v[112:115], v[172:175], v[192:195], v[112:115]
	v_mfma_f32_16x16x32_bf16 v[104:107], v[180:183], v[192:195], v[104:107]
	v_mfma_f32_16x16x32_bf16 v[96:99], v[172:175], v[200:203], v[96:99]
	v_mfma_f32_16x16x32_bf16 v[88:91], v[180:183], v[200:203], v[88:91]
	v_mfma_f32_16x16x32_bf16 v[80:83], v[172:175], v[208:211], v[80:83]
	v_mfma_f32_16x16x32_bf16 v[72:75], v[180:183], v[208:211], v[72:75]
	v_mfma_f32_16x16x32_bf16 v[68:71], v[172:175], v[216:219], v[68:71]
	v_mfma_f32_16x16x32_bf16 v[64:67], v[180:183], v[216:219], v[64:67]
	s_barrier
	s_add_i32 s64, s87, s68
	s_mov_b32 m0, s64
	ds_read_b128 v[184:187], v155 offset:49152
	ds_read_b128 v[192:195], v155 offset:50176
	ds_read_b128 v[196:199], v155 offset:51200
	ds_read_b128 v[200:203], v155 offset:52224
	ds_read_b128 v[204:207], v155 offset:53248
	ds_read_b128 v[208:211], v155 offset:54272
	ds_read_b128 v[212:215], v155 offset:55296
	ds_read_b128 v[216:219], v155 offset:56320
	global_load_lds_dwordx4 v132, s[98:99]
	s_add_i32 m0, s64, 0x2000
	s_add_u32 s62, s62, 0x40080
	s_addc_u32 s63, s63, 0
	s_add_i32 s64, s88, s68
	global_load_lds_dwordx4 v128, s[98:99]
	s_mov_b32 m0, s64
	s_nop 0
	global_load_lds_dwordx4 v132, s[62:63]
	s_add_i32 m0, s64, 0x2000
	s_nop 0
	global_load_lds_dwordx4 v128, s[62:63]
	s_mov_b32 m0, s33
	s_nop 0
	global_load_lds_dwordx4 v134, s[100:101]
	s_mov_b32 m0, s74
	s_nop 0
	global_load_lds_dwordx4 v130, s[100:101]
	s_waitcnt vmcnt(8)
	s_waitcnt lgkmcnt(0)
	s_barrier
	v_mfma_f32_16x16x32_bf16 v[60:63], v[146:149], v[184:187], v[60:63]
	v_mfma_f32_16x16x32_bf16 v[56:59], v[160:163], v[184:187], v[56:59]
	v_mfma_f32_16x16x32_bf16 v[52:55], v[146:149], v[196:199], v[52:55]
	v_mfma_f32_16x16x32_bf16 v[44:47], v[160:163], v[196:199], v[44:47]
	v_mfma_f32_16x16x32_bf16 v[36:39], v[146:149], v[204:207], v[36:39]
	v_mfma_f32_16x16x32_bf16 v[28:31], v[160:163], v[204:207], v[28:31]
	v_mfma_f32_16x16x32_bf16 v[20:23], v[146:149], v[212:215], v[20:23]
	v_mfma_f32_16x16x32_bf16 v[12:15], v[160:163], v[212:215], v[12:15]
	v_mfma_f32_16x16x32_bf16 v[60:63], v[156:159], v[192:195], v[60:63]
	v_mfma_f32_16x16x32_bf16 v[56:59], v[164:167], v[192:195], v[56:59]
	v_mfma_f32_16x16x32_bf16 v[52:55], v[156:159], v[200:203], v[52:55]
	v_mfma_f32_16x16x32_bf16 v[44:47], v[164:167], v[200:203], v[44:47]
	v_mfma_f32_16x16x32_bf16 v[36:39], v[156:159], v[208:211], v[36:39]
	v_mfma_f32_16x16x32_bf16 v[28:31], v[164:167], v[208:211], v[28:31]
	v_mfma_f32_16x16x32_bf16 v[20:23], v[156:159], v[216:219], v[20:23]
	v_mfma_f32_16x16x32_bf16 v[12:15], v[164:167], v[216:219], v[12:15]
	v_mfma_f32_16x16x32_bf16 v[48:51], v[168:171], v[184:187], v[48:51]
	v_mfma_f32_16x16x32_bf16 v[40:43], v[176:179], v[184:187], v[40:43]
	v_mfma_f32_16x16x32_bf16 v[32:35], v[168:171], v[196:199], v[32:35]
	v_mfma_f32_16x16x32_bf16 v[24:27], v[176:179], v[196:199], v[24:27]
	v_mfma_f32_16x16x32_bf16 v[16:19], v[168:171], v[204:207], v[16:19]
	v_mfma_f32_16x16x32_bf16 v[8:11], v[176:179], v[204:207], v[8:11]
	v_mfma_f32_16x16x32_bf16 v[4:7], v[168:171], v[212:215], v[4:7]
	v_mfma_f32_16x16x32_bf16 v[0:3], v[176:179], v[212:215], v[0:3]
	v_mfma_f32_16x16x32_bf16 v[48:51], v[172:175], v[192:195], v[48:51]
	v_mfma_f32_16x16x32_bf16 v[40:43], v[180:183], v[192:195], v[40:43]
	v_mfma_f32_16x16x32_bf16 v[32:35], v[172:175], v[200:203], v[32:35]
	v_mfma_f32_16x16x32_bf16 v[24:27], v[180:183], v[200:203], v[24:27]
	v_mfma_f32_16x16x32_bf16 v[16:19], v[172:175], v[208:211], v[16:19]
	v_mfma_f32_16x16x32_bf16 v[8:11], v[180:183], v[208:211], v[8:11]
	v_mfma_f32_16x16x32_bf16 v[4:7], v[172:175], v[216:219], v[4:7]
	v_mfma_f32_16x16x32_bf16 v[0:3], v[180:183], v[216:219], v[0:3]
	s_barrier
	s_add_i32 s86, s86, 2
	s_add_u32 s60, s60, 0x100
	s_addc_u32 s61, s61, 0
	s_add_u32 s84, s84, 0x100
	s_addc_u32 s85, s85, 0
	s_cmp_gt_u32 s86, 13
	s_cbranch_scc0 .LBB0_272

.LBB0_302:
	ds_read_b128 v[152:155], v149
	ds_read_b128 v[156:159], v149 offset:1024
	ds_read_b128 v[160:163], v149 offset:2048
	ds_read_b128 v[164:167], v149 offset:3072
	ds_read_b128 v[168:171], v150
	ds_read_b128 v[172:175], v150 offset:1024
	ds_read_b128 v[176:179], v150 offset:2048
	ds_read_b128 v[180:183], v150 offset:3072
	s_add_u32 s38, s36, 0xfffc0080
	s_addc_u32 s39, s37, -1
	s_cmp_eq_u32 s75, 12
	s_cselect_b32 s41, s27, s39
	s_cselect_b32 s40, s55, s38
	s_cselect_b32 s39, s25, s74
	s_cselect_b32 s38, s72, s73
	v_lshl_add_u64 v[144:145], s[36:37], 0, v[136:137]
	s_add_i32 m0, s35, 0xc000
	ds_read_b128 v[184:187], v151
	ds_read_b128 v[192:195], v151 offset:1024
	ds_read_b128 v[196:199], v151 offset:2048
	ds_read_b128 v[200:203], v151 offset:3072
	ds_read_b128 v[204:207], v151 offset:4096
	ds_read_b128 v[208:211], v151 offset:5120
	ds_read_b128 v[212:215], v151 offset:6144
	ds_read_b128 v[216:219], v151 offset:7168
	global_load_lds_dwordx4 v[144:145], off
	s_add_i32 m0, s35, 0xe000
	s_nop 0
	global_load_lds_dwordx4 v138, s[36:37]
	s_waitcnt vmcnt(8)
	s_waitcnt lgkmcnt(0)
	s_barrier
	v_mfma_f32_16x16x32_bf16 v[124:127], v[152:155], v[184:187], v[124:127]
	v_mfma_f32_16x16x32_bf16 v[120:123], v[160:163], v[184:187], v[120:123]
	v_mfma_f32_16x16x32_bf16 v[116:119], v[152:155], v[196:199], v[116:119]
	v_mfma_f32_16x16x32_bf16 v[108:111], v[160:163], v[196:199], v[108:111]
	v_mfma_f32_16x16x32_bf16 v[100:103], v[152:155], v[204:207], v[100:103]
	v_mfma_f32_16x16x32_bf16 v[92:95], v[160:163], v[204:207], v[92:95]
	v_mfma_f32_16x16x32_bf16 v[84:87], v[152:155], v[212:215], v[84:87]
	v_mfma_f32_16x16x32_bf16 v[76:79], v[160:163], v[212:215], v[76:79]
	v_mfma_f32_16x16x32_bf16 v[124:127], v[156:159], v[192:195], v[124:127]
	v_mfma_f32_16x16x32_bf16 v[120:123], v[164:167], v[192:195], v[120:123]
	v_mfma_f32_16x16x32_bf16 v[116:119], v[156:159], v[200:203], v[116:119]
	v_mfma_f32_16x16x32_bf16 v[108:111], v[164:167], v[200:203], v[108:111]
	v_mfma_f32_16x16x32_bf16 v[100:103], v[156:159], v[208:211], v[100:103]
	v_mfma_f32_16x16x32_bf16 v[92:95], v[164:167], v[208:211], v[92:95]
	v_mfma_f32_16x16x32_bf16 v[84:87], v[156:159], v[216:219], v[84:87]
	v_mfma_f32_16x16x32_bf16 v[76:79], v[164:167], v[216:219], v[76:79]
	v_mfma_f32_16x16x32_bf16 v[112:115], v[168:171], v[184:187], v[112:115]
	v_mfma_f32_16x16x32_bf16 v[104:107], v[176:179], v[184:187], v[104:107]
	v_mfma_f32_16x16x32_bf16 v[96:99], v[168:171], v[196:199], v[96:99]
	v_mfma_f32_16x16x32_bf16 v[88:91], v[176:179], v[196:199], v[88:91]
	v_mfma_f32_16x16x32_bf16 v[80:83], v[168:171], v[204:207], v[80:83]
	v_mfma_f32_16x16x32_bf16 v[72:75], v[176:179], v[204:207], v[72:75]
	v_mfma_f32_16x16x32_bf16 v[68:71], v[168:171], v[212:215], v[68:71]
	v_mfma_f32_16x16x32_bf16 v[64:67], v[176:179], v[212:215], v[64:67]
	v_mfma_f32_16x16x32_bf16 v[112:115], v[172:175], v[192:195], v[112:115]
	v_mfma_f32_16x16x32_bf16 v[104:107], v[180:183], v[192:195], v[104:107]
	v_mfma_f32_16x16x32_bf16 v[96:99], v[172:175], v[200:203], v[96:99]
	v_mfma_f32_16x16x32_bf16 v[88:91], v[180:183], v[200:203], v[88:91]
	v_mfma_f32_16x16x32_bf16 v[80:83], v[172:175], v[208:211], v[80:83]
	v_mfma_f32_16x16x32_bf16 v[72:75], v[180:183], v[208:211], v[72:75]
	v_mfma_f32_16x16x32_bf16 v[68:71], v[172:175], v[216:219], v[68:71]
	v_mfma_f32_16x16x32_bf16 v[64:67], v[180:183], v[216:219], v[64:67]
	s_barrier
	s_add_i32 s76, s66, s53
	s_add_u32 s98, s38, 0x80
	s_addc_u32 s99, s39, 0
	s_mov_b32 m0, s76
	ds_read_b128 v[184:187], v151 offset:16384
	ds_read_b128 v[192:195], v151 offset:17408
	ds_read_b128 v[196:199], v151 offset:18432
	ds_read_b128 v[200:203], v151 offset:19456
	ds_read_b128 v[204:207], v151 offset:20480
	ds_read_b128 v[208:211], v151 offset:21504
	ds_read_b128 v[212:215], v151 offset:22528
	ds_read_b128 v[216:219], v151 offset:23552
	global_load_lds_dwordx4 v130, s[38:39]
	s_add_i32 m0, s76, 0x2000
	s_add_u32 s76, s38, 0x40000
	s_addc_u32 s77, s39, 0
	s_add_i32 s80, s67, s53
	global_load_lds_dwordx4 v134, s[38:39]
	s_mov_b32 m0, s80
	s_add_u32 s100, s40, 0x80
	s_addc_u32 s101, s41, 0
	global_load_lds_dwordx4 v130, s[76:77]
	s_add_i32 m0, s80, 0x2000
	s_nop 0
	global_load_lds_dwordx4 v134, s[76:77]
	s_mov_b32 m0, s35
	s_nop 0
	global_load_lds_dwordx4 v128, s[40:41]
	s_mov_b32 m0, s33
	s_nop 0
	global_load_lds_dwordx4 v132, s[40:41]
	s_waitcnt vmcnt(8)
	s_waitcnt lgkmcnt(0)
	s_barrier
	v_mfma_f32_16x16x32_bf16 v[60:63], v[152:155], v[184:187], v[60:63]
	v_mfma_f32_16x16x32_bf16 v[56:59], v[160:163], v[184:187], v[56:59]
	v_mfma_f32_16x16x32_bf16 v[52:55], v[152:155], v[196:199], v[52:55]
	v_mfma_f32_16x16x32_bf16 v[44:47], v[160:163], v[196:199], v[44:47]
	v_mfma_f32_16x16x32_bf16 v[36:39], v[152:155], v[204:207], v[36:39]
	v_mfma_f32_16x16x32_bf16 v[28:31], v[160:163], v[204:207], v[28:31]
	v_mfma_f32_16x16x32_bf16 v[20:23], v[152:155], v[212:215], v[20:23]
	v_mfma_f32_16x16x32_bf16 v[12:15], v[160:163], v[212:215], v[12:15]
	v_mfma_f32_16x16x32_bf16 v[60:63], v[156:159], v[192:195], v[60:63]
	v_mfma_f32_16x16x32_bf16 v[56:59], v[164:167], v[192:195], v[56:59]
	v_mfma_f32_16x16x32_bf16 v[52:55], v[156:159], v[200:203], v[52:55]
	v_mfma_f32_16x16x32_bf16 v[44:47], v[164:167], v[200:203], v[44:47]
	v_mfma_f32_16x16x32_bf16 v[36:39], v[156:159], v[208:211], v[36:39]
	v_mfma_f32_16x16x32_bf16 v[28:31], v[164:167], v[208:211], v[28:31]
	v_mfma_f32_16x16x32_bf16 v[20:23], v[156:159], v[216:219], v[20:23]
	v_mfma_f32_16x16x32_bf16 v[12:15], v[164:167], v[216:219], v[12:15]
	v_mfma_f32_16x16x32_bf16 v[48:51], v[168:171], v[184:187], v[48:51]
	v_mfma_f32_16x16x32_bf16 v[40:43], v[176:179], v[184:187], v[40:43]
	v_mfma_f32_16x16x32_bf16 v[32:35], v[168:171], v[196:199], v[32:35]
	v_mfma_f32_16x16x32_bf16 v[24:27], v[176:179], v[196:199], v[24:27]
	v_mfma_f32_16x16x32_bf16 v[16:19], v[168:171], v[204:207], v[16:19]
	v_mfma_f32_16x16x32_bf16 v[8:11], v[176:179], v[204:207], v[8:11]
	v_mfma_f32_16x16x32_bf16 v[4:7], v[168:171], v[212:215], v[4:7]
	v_mfma_f32_16x16x32_bf16 v[0:3], v[176:179], v[212:215], v[0:3]
	v_mfma_f32_16x16x32_bf16 v[48:51], v[172:175], v[192:195], v[48:51]
	v_mfma_f32_16x16x32_bf16 v[40:43], v[180:183], v[192:195], v[40:43]
	v_mfma_f32_16x16x32_bf16 v[32:35], v[172:175], v[200:203], v[32:35]
	v_mfma_f32_16x16x32_bf16 v[24:27], v[180:183], v[200:203], v[24:27]
	v_mfma_f32_16x16x32_bf16 v[16:19], v[172:175], v[208:211], v[16:19]
	v_mfma_f32_16x16x32_bf16 v[8:11], v[180:183], v[208:211], v[8:11]
	v_mfma_f32_16x16x32_bf16 v[4:7], v[172:175], v[216:219], v[4:7]
	v_mfma_f32_16x16x32_bf16 v[0:3], v[180:183], v[216:219], v[0:3]
	s_barrier
	s_add_i32 s76, 0, 0x18000
	s_add_i32 s77, 0, 0x1c000
	v_add_u32_e32 v164, s76, v147
	v_add_u32_e32 v180, s77, v147
	ds_read_b128 v[152:155], v164
	ds_read_b128 v[156:159], v164 offset:1024
	ds_read_b128 v[160:163], v164 offset:2048
	ds_read_b128 v[164:167], v164 offset:3072
	ds_read_b128 v[168:171], v180
	ds_read_b128 v[172:175], v180 offset:1024
	ds_read_b128 v[176:179], v180 offset:2048
	ds_read_b128 v[180:183], v180 offset:3072
	s_add_u32 s40, s40, 0x40000
	s_addc_u32 s41, s41, 0
	s_mov_b32 m0, s60
	ds_read_b128 v[184:187], v151 offset:32768
	ds_read_b128 v[192:195], v151 offset:33792
	ds_read_b128 v[196:199], v151 offset:34816
	ds_read_b128 v[200:203], v151 offset:35840
	ds_read_b128 v[204:207], v151 offset:36864
	ds_read_b128 v[208:211], v151 offset:37888
	ds_read_b128 v[212:215], v151 offset:38912
	ds_read_b128 v[216:219], v151 offset:39936
	global_load_lds_dwordx4 v128, s[40:41]
	s_mov_b32 m0, s61
	s_nop 0
	global_load_lds_dwordx4 v132, s[40:41]
	s_waitcnt vmcnt(8)
	s_waitcnt lgkmcnt(0)
	s_barrier
	v_mfma_f32_16x16x32_bf16 v[124:127], v[152:155], v[184:187], v[124:127]
	v_mfma_f32_16x16x32_bf16 v[120:123], v[160:163], v[184:187], v[120:123]
	v_mfma_f32_16x16x32_bf16 v[116:119], v[152:155], v[196:199], v[116:119]
	v_mfma_f32_16x16x32_bf16 v[108:111], v[160:163], v[196:199], v[108:111]
	v_mfma_f32_16x16x32_bf16 v[100:103], v[152:155], v[204:207], v[100:103]
	v_mfma_f32_16x16x32_bf16 v[92:95], v[160:163], v[204:207], v[92:95]
	v_mfma_f32_16x16x32_bf16 v[84:87], v[152:155], v[212:215], v[84:87]
	v_mfma_f32_16x16x32_bf16 v[76:79], v[160:163], v[212:215], v[76:79]
	v_mfma_f32_16x16x32_bf16 v[124:127], v[156:159], v[192:195], v[124:127]
	v_mfma_f32_16x16x32_bf16 v[120:123], v[164:167], v[192:195], v[120:123]
	v_mfma_f32_16x16x32_bf16 v[116:119], v[156:159], v[200:203], v[116:119]
	v_mfma_f32_16x16x32_bf16 v[108:111], v[164:167], v[200:203], v[108:111]
	v_mfma_f32_16x16x32_bf16 v[100:103], v[156:159], v[208:211], v[100:103]
	v_mfma_f32_16x16x32_bf16 v[92:95], v[164:167], v[208:211], v[92:95]
	v_mfma_f32_16x16x32_bf16 v[84:87], v[156:159], v[216:219], v[84:87]
	v_mfma_f32_16x16x32_bf16 v[76:79], v[164:167], v[216:219], v[76:79]
	v_mfma_f32_16x16x32_bf16 v[112:115], v[168:171], v[184:187], v[112:115]
	v_mfma_f32_16x16x32_bf16 v[104:107], v[176:179], v[184:187], v[104:107]
	v_mfma_f32_16x16x32_bf16 v[96:99], v[168:171], v[196:199], v[96:99]
	v_mfma_f32_16x16x32_bf16 v[88:91], v[176:179], v[196:199], v[88:91]
	v_mfma_f32_16x16x32_bf16 v[80:83], v[168:171], v[204:207], v[80:83]
	v_mfma_f32_16x16x32_bf16 v[72:75], v[176:179], v[204:207], v[72:75]
	v_mfma_f32_16x16x32_bf16 v[68:71], v[168:171], v[212:215], v[68:71]
	v_mfma_f32_16x16x32_bf16 v[64:67], v[176:179], v[212:215], v[64:67]
	v_mfma_f32_16x16x32_bf16 v[112:115], v[172:175], v[192:195], v[112:115]
	v_mfma_f32_16x16x32_bf16 v[104:107], v[180:183], v[192:195], v[104:107]
	v_mfma_f32_16x16x32_bf16 v[96:99], v[172:175], v[200:203], v[96:99]
	v_mfma_f32_16x16x32_bf16 v[88:91], v[180:183], v[200:203], v[88:91]
	v_mfma_f32_16x16x32_bf16 v[80:83], v[172:175], v[208:211], v[80:83]
	v_mfma_f32_16x16x32_bf16 v[72:75], v[180:183], v[208:211], v[72:75]
	v_mfma_f32_16x16x32_bf16 v[68:71], v[172:175], v[216:219], v[68:71]
	v_mfma_f32_16x16x32_bf16 v[64:67], v[180:183], v[216:219], v[64:67]
	s_barrier
	s_add_i32 s40, s76, s53
	s_mov_b32 m0, s40
	ds_read_b128 v[184:187], v151 offset:49152
	ds_read_b128 v[192:195], v151 offset:50176
	ds_read_b128 v[196:199], v151 offset:51200
	ds_read_b128 v[200:203], v151 offset:52224
	ds_read_b128 v[204:207], v151 offset:53248
	ds_read_b128 v[208:211], v151 offset:54272
	ds_read_b128 v[212:215], v151 offset:55296
	ds_read_b128 v[216:219], v151 offset:56320
	global_load_lds_dwordx4 v130, s[98:99]
	s_add_i32 m0, s40, 0x2000
	s_add_u32 s38, s38, 0x40080
	s_addc_u32 s39, s39, 0
	s_add_i32 s40, s77, s53
	global_load_lds_dwordx4 v134, s[98:99]
	s_mov_b32 m0, s40
	s_nop 0
	global_load_lds_dwordx4 v130, s[38:39]
	s_add_i32 m0, s40, 0x2000
	s_nop 0
	global_load_lds_dwordx4 v134, s[38:39]
	s_mov_b32 m0, s63
	s_nop 0
	global_load_lds_dwordx4 v128, s[100:101]
	s_mov_b32 m0, s64
	s_nop 0
	global_load_lds_dwordx4 v132, s[100:101]
	s_waitcnt vmcnt(8)
	s_waitcnt lgkmcnt(0)
	s_barrier
	v_mfma_f32_16x16x32_bf16 v[60:63], v[152:155], v[184:187], v[60:63]
	v_mfma_f32_16x16x32_bf16 v[56:59], v[160:163], v[184:187], v[56:59]
	v_mfma_f32_16x16x32_bf16 v[52:55], v[152:155], v[196:199], v[52:55]
	v_mfma_f32_16x16x32_bf16 v[44:47], v[160:163], v[196:199], v[44:47]
	v_mfma_f32_16x16x32_bf16 v[36:39], v[152:155], v[204:207], v[36:39]
	v_mfma_f32_16x16x32_bf16 v[28:31], v[160:163], v[204:207], v[28:31]
	v_mfma_f32_16x16x32_bf16 v[20:23], v[152:155], v[212:215], v[20:23]
	v_mfma_f32_16x16x32_bf16 v[12:15], v[160:163], v[212:215], v[12:15]
	v_mfma_f32_16x16x32_bf16 v[60:63], v[156:159], v[192:195], v[60:63]
	v_mfma_f32_16x16x32_bf16 v[56:59], v[164:167], v[192:195], v[56:59]
	v_mfma_f32_16x16x32_bf16 v[52:55], v[156:159], v[200:203], v[52:55]
	v_mfma_f32_16x16x32_bf16 v[44:47], v[164:167], v[200:203], v[44:47]
	v_mfma_f32_16x16x32_bf16 v[36:39], v[156:159], v[208:211], v[36:39]
	v_mfma_f32_16x16x32_bf16 v[28:31], v[164:167], v[208:211], v[28:31]
	v_mfma_f32_16x16x32_bf16 v[20:23], v[156:159], v[216:219], v[20:23]
	v_mfma_f32_16x16x32_bf16 v[12:15], v[164:167], v[216:219], v[12:15]
	v_mfma_f32_16x16x32_bf16 v[48:51], v[168:171], v[184:187], v[48:51]
	v_mfma_f32_16x16x32_bf16 v[40:43], v[176:179], v[184:187], v[40:43]
	v_mfma_f32_16x16x32_bf16 v[32:35], v[168:171], v[196:199], v[32:35]
	v_mfma_f32_16x16x32_bf16 v[24:27], v[176:179], v[196:199], v[24:27]
	v_mfma_f32_16x16x32_bf16 v[16:19], v[168:171], v[204:207], v[16:19]
	v_mfma_f32_16x16x32_bf16 v[8:11], v[176:179], v[204:207], v[8:11]
	v_mfma_f32_16x16x32_bf16 v[4:7], v[168:171], v[212:215], v[4:7]
	v_mfma_f32_16x16x32_bf16 v[0:3], v[176:179], v[212:215], v[0:3]
	v_mfma_f32_16x16x32_bf16 v[48:51], v[172:175], v[192:195], v[48:51]
	v_mfma_f32_16x16x32_bf16 v[40:43], v[180:183], v[192:195], v[40:43]
	v_mfma_f32_16x16x32_bf16 v[32:35], v[172:175], v[200:203], v[32:35]
	v_mfma_f32_16x16x32_bf16 v[24:27], v[180:183], v[200:203], v[24:27]
	v_mfma_f32_16x16x32_bf16 v[16:19], v[172:175], v[208:211], v[16:19]
	v_mfma_f32_16x16x32_bf16 v[8:11], v[180:183], v[208:211], v[8:11]
	v_mfma_f32_16x16x32_bf16 v[4:7], v[172:175], v[216:219], v[4:7]
	v_mfma_f32_16x16x32_bf16 v[0:3], v[180:183], v[216:219], v[0:3]
	s_barrier
	s_add_i32 s75, s75, 2
	s_add_u32 s36, s36, 0x100
	s_addc_u32 s37, s37, 0
	s_add_u32 s73, s73, 0x100
	s_addc_u32 s74, s74, 0
	s_cmp_gt_u32 s75, 13
	s_cbranch_scc0 .LBB0_302

.LBB0_700:
	ds_read_b128 v[152:155], v149
	ds_read_b128 v[156:159], v149 offset:1024
	ds_read_b128 v[160:163], v149 offset:2048
	ds_read_b128 v[164:167], v149 offset:3072
	ds_read_b128 v[168:171], v150
	ds_read_b128 v[172:175], v150 offset:1024
	ds_read_b128 v[176:179], v150 offset:2048
	ds_read_b128 v[180:183], v150 offset:3072
	s_add_u32 s38, s34, 0xfffc0080
	s_addc_u32 s39, s35, -1
	s_cmp_eq_u32 s75, 12
	s_cselect_b32 s41, s25, s39
	s_cselect_b32 s40, s55, s38
	s_cselect_b32 s39, s23, s74
	s_cselect_b32 s38, s72, s73
	s_add_i32 m0, s31, 0xc000
	ds_read_b128 v[184:187], v151
	ds_read_b128 v[192:195], v151 offset:1024
	ds_read_b128 v[196:199], v151 offset:2048
	ds_read_b128 v[200:203], v151 offset:3072
	ds_read_b128 v[204:207], v151 offset:4096
	ds_read_b128 v[208:211], v151 offset:5120
	ds_read_b128 v[212:215], v151 offset:6144
	ds_read_b128 v[216:219], v151 offset:7168
	global_load_lds_dwordx4 v136, s[34:35]
	s_add_i32 m0, s31, 0xe000
	s_nop 0
	global_load_lds_dwordx4 v138, s[34:35]
	s_waitcnt vmcnt(8)
	s_waitcnt lgkmcnt(0)
	s_barrier
	v_mfma_f32_16x16x32_bf16 v[124:127], v[152:155], v[184:187], v[124:127]
	v_mfma_f32_16x16x32_bf16 v[120:123], v[160:163], v[184:187], v[120:123]
	v_mfma_f32_16x16x32_bf16 v[116:119], v[152:155], v[196:199], v[116:119]
	v_mfma_f32_16x16x32_bf16 v[108:111], v[160:163], v[196:199], v[108:111]
	v_mfma_f32_16x16x32_bf16 v[100:103], v[152:155], v[204:207], v[100:103]
	v_mfma_f32_16x16x32_bf16 v[92:95], v[160:163], v[204:207], v[92:95]
	v_mfma_f32_16x16x32_bf16 v[84:87], v[152:155], v[212:215], v[84:87]
	v_mfma_f32_16x16x32_bf16 v[76:79], v[160:163], v[212:215], v[76:79]
	v_mfma_f32_16x16x32_bf16 v[124:127], v[156:159], v[192:195], v[124:127]
	v_mfma_f32_16x16x32_bf16 v[120:123], v[164:167], v[192:195], v[120:123]
	v_mfma_f32_16x16x32_bf16 v[116:119], v[156:159], v[200:203], v[116:119]
	v_mfma_f32_16x16x32_bf16 v[108:111], v[164:167], v[200:203], v[108:111]
	v_mfma_f32_16x16x32_bf16 v[100:103], v[156:159], v[208:211], v[100:103]
	v_mfma_f32_16x16x32_bf16 v[92:95], v[164:167], v[208:211], v[92:95]
	v_mfma_f32_16x16x32_bf16 v[84:87], v[156:159], v[216:219], v[84:87]
	v_mfma_f32_16x16x32_bf16 v[76:79], v[164:167], v[216:219], v[76:79]
	v_mfma_f32_16x16x32_bf16 v[112:115], v[168:171], v[184:187], v[112:115]
	v_mfma_f32_16x16x32_bf16 v[104:107], v[176:179], v[184:187], v[104:107]
	v_mfma_f32_16x16x32_bf16 v[96:99], v[168:171], v[196:199], v[96:99]
	v_mfma_f32_16x16x32_bf16 v[88:91], v[176:179], v[196:199], v[88:91]
	v_mfma_f32_16x16x32_bf16 v[80:83], v[168:171], v[204:207], v[80:83]
	v_mfma_f32_16x16x32_bf16 v[72:75], v[176:179], v[204:207], v[72:75]
	v_mfma_f32_16x16x32_bf16 v[68:71], v[168:171], v[212:215], v[68:71]
	v_mfma_f32_16x16x32_bf16 v[64:67], v[176:179], v[212:215], v[64:67]
	v_mfma_f32_16x16x32_bf16 v[112:115], v[172:175], v[192:195], v[112:115]
	v_mfma_f32_16x16x32_bf16 v[104:107], v[180:183], v[192:195], v[104:107]
	v_mfma_f32_16x16x32_bf16 v[96:99], v[172:175], v[200:203], v[96:99]
	v_mfma_f32_16x16x32_bf16 v[88:91], v[180:183], v[200:203], v[88:91]
	v_mfma_f32_16x16x32_bf16 v[80:83], v[172:175], v[208:211], v[80:83]
	v_mfma_f32_16x16x32_bf16 v[72:75], v[180:183], v[208:211], v[72:75]
	v_mfma_f32_16x16x32_bf16 v[68:71], v[172:175], v[216:219], v[68:71]
	v_mfma_f32_16x16x32_bf16 v[64:67], v[180:183], v[216:219], v[64:67]
	s_barrier
	s_add_i32 s76, s66, s53
	s_add_u32 s98, s38, 0x80
	s_addc_u32 s99, s39, 0
	s_mov_b32 m0, s76
	ds_read_b128 v[184:187], v151 offset:16384
	ds_read_b128 v[192:195], v151 offset:17408
	ds_read_b128 v[196:199], v151 offset:18432
	ds_read_b128 v[200:203], v151 offset:19456
	ds_read_b128 v[204:207], v151 offset:20480
	ds_read_b128 v[208:211], v151 offset:21504
	ds_read_b128 v[212:215], v151 offset:22528
	ds_read_b128 v[216:219], v151 offset:23552
	global_load_lds_dwordx4 v130, s[38:39]
	s_add_i32 m0, s76, 0x2000
	s_add_u32 s76, s38, 0x40000
	s_addc_u32 s77, s39, 0
	s_add_i32 s79, s67, s53
	global_load_lds_dwordx4 v134, s[38:39]
	s_mov_b32 m0, s79
	s_add_u32 s100, s40, 0x80
	s_addc_u32 s101, s41, 0
	global_load_lds_dwordx4 v130, s[76:77]
	s_add_i32 m0, s79, 0x2000
	s_nop 0
	global_load_lds_dwordx4 v134, s[76:77]
	s_mov_b32 m0, s31
	s_nop 0
	global_load_lds_dwordx4 v128, s[40:41]
	s_mov_b32 m0, s33
	s_nop 0
	global_load_lds_dwordx4 v132, s[40:41]
	s_waitcnt vmcnt(8)
	s_waitcnt lgkmcnt(0)
	s_barrier
	v_mfma_f32_16x16x32_bf16 v[60:63], v[152:155], v[184:187], v[60:63]
	v_mfma_f32_16x16x32_bf16 v[56:59], v[160:163], v[184:187], v[56:59]
	v_mfma_f32_16x16x32_bf16 v[52:55], v[152:155], v[196:199], v[52:55]
	v_mfma_f32_16x16x32_bf16 v[44:47], v[160:163], v[196:199], v[44:47]
	v_mfma_f32_16x16x32_bf16 v[36:39], v[152:155], v[204:207], v[36:39]
	v_mfma_f32_16x16x32_bf16 v[28:31], v[160:163], v[204:207], v[28:31]
	v_mfma_f32_16x16x32_bf16 v[20:23], v[152:155], v[212:215], v[20:23]
	v_mfma_f32_16x16x32_bf16 v[12:15], v[160:163], v[212:215], v[12:15]
	v_mfma_f32_16x16x32_bf16 v[60:63], v[156:159], v[192:195], v[60:63]
	v_mfma_f32_16x16x32_bf16 v[56:59], v[164:167], v[192:195], v[56:59]
	v_mfma_f32_16x16x32_bf16 v[52:55], v[156:159], v[200:203], v[52:55]
	v_mfma_f32_16x16x32_bf16 v[44:47], v[164:167], v[200:203], v[44:47]
	v_mfma_f32_16x16x32_bf16 v[36:39], v[156:159], v[208:211], v[36:39]
	v_mfma_f32_16x16x32_bf16 v[28:31], v[164:167], v[208:211], v[28:31]
	v_mfma_f32_16x16x32_bf16 v[20:23], v[156:159], v[216:219], v[20:23]
	v_mfma_f32_16x16x32_bf16 v[12:15], v[164:167], v[216:219], v[12:15]
	v_mfma_f32_16x16x32_bf16 v[48:51], v[168:171], v[184:187], v[48:51]
	v_mfma_f32_16x16x32_bf16 v[40:43], v[176:179], v[184:187], v[40:43]
	v_mfma_f32_16x16x32_bf16 v[32:35], v[168:171], v[196:199], v[32:35]
	v_mfma_f32_16x16x32_bf16 v[24:27], v[176:179], v[196:199], v[24:27]
	v_mfma_f32_16x16x32_bf16 v[16:19], v[168:171], v[204:207], v[16:19]
	v_mfma_f32_16x16x32_bf16 v[8:11], v[176:179], v[204:207], v[8:11]
	v_mfma_f32_16x16x32_bf16 v[4:7], v[168:171], v[212:215], v[4:7]
	v_mfma_f32_16x16x32_bf16 v[0:3], v[176:179], v[212:215], v[0:3]
	v_mfma_f32_16x16x32_bf16 v[48:51], v[172:175], v[192:195], v[48:51]
	v_mfma_f32_16x16x32_bf16 v[40:43], v[180:183], v[192:195], v[40:43]
	v_mfma_f32_16x16x32_bf16 v[32:35], v[172:175], v[200:203], v[32:35]
	v_mfma_f32_16x16x32_bf16 v[24:27], v[180:183], v[200:203], v[24:27]
	v_mfma_f32_16x16x32_bf16 v[16:19], v[172:175], v[208:211], v[16:19]
	v_mfma_f32_16x16x32_bf16 v[8:11], v[180:183], v[208:211], v[8:11]
	v_mfma_f32_16x16x32_bf16 v[4:7], v[172:175], v[216:219], v[4:7]
	v_mfma_f32_16x16x32_bf16 v[0:3], v[180:183], v[216:219], v[0:3]
	s_barrier
	s_add_i32 s76, 0, 0x18000
	s_add_i32 s77, 0, 0x1c000
	v_add_u32_e32 v164, s76, v147
	v_add_u32_e32 v180, s77, v147
	ds_read_b128 v[152:155], v164
	ds_read_b128 v[156:159], v164 offset:1024
	ds_read_b128 v[160:163], v164 offset:2048
	ds_read_b128 v[164:167], v164 offset:3072
	ds_read_b128 v[168:171], v180
	ds_read_b128 v[172:175], v180 offset:1024
	ds_read_b128 v[176:179], v180 offset:2048
	ds_read_b128 v[180:183], v180 offset:3072
	s_add_u32 s40, s40, 0x40000
	s_addc_u32 s41, s41, 0
	s_mov_b32 m0, s60
	ds_read_b128 v[184:187], v151 offset:32768
	ds_read_b128 v[192:195], v151 offset:33792
	ds_read_b128 v[196:199], v151 offset:34816
	ds_read_b128 v[200:203], v151 offset:35840
	ds_read_b128 v[204:207], v151 offset:36864
	ds_read_b128 v[208:211], v151 offset:37888
	ds_read_b128 v[212:215], v151 offset:38912
	ds_read_b128 v[216:219], v151 offset:39936
	global_load_lds_dwordx4 v128, s[40:41]
	s_mov_b32 m0, s61
	s_nop 0
	global_load_lds_dwordx4 v132, s[40:41]
	s_waitcnt vmcnt(8)
	s_waitcnt lgkmcnt(0)
	s_barrier
	v_mfma_f32_16x16x32_bf16 v[124:127], v[152:155], v[184:187], v[124:127]
	v_mfma_f32_16x16x32_bf16 v[120:123], v[160:163], v[184:187], v[120:123]
	v_mfma_f32_16x16x32_bf16 v[116:119], v[152:155], v[196:199], v[116:119]
	v_mfma_f32_16x16x32_bf16 v[108:111], v[160:163], v[196:199], v[108:111]
	v_mfma_f32_16x16x32_bf16 v[100:103], v[152:155], v[204:207], v[100:103]
	v_mfma_f32_16x16x32_bf16 v[92:95], v[160:163], v[204:207], v[92:95]
	v_mfma_f32_16x16x32_bf16 v[84:87], v[152:155], v[212:215], v[84:87]
	v_mfma_f32_16x16x32_bf16 v[76:79], v[160:163], v[212:215], v[76:79]
	v_mfma_f32_16x16x32_bf16 v[124:127], v[156:159], v[192:195], v[124:127]
	v_mfma_f32_16x16x32_bf16 v[120:123], v[164:167], v[192:195], v[120:123]
	v_mfma_f32_16x16x32_bf16 v[116:119], v[156:159], v[200:203], v[116:119]
	v_mfma_f32_16x16x32_bf16 v[108:111], v[164:167], v[200:203], v[108:111]
	v_mfma_f32_16x16x32_bf16 v[100:103], v[156:159], v[208:211], v[100:103]
	v_mfma_f32_16x16x32_bf16 v[92:95], v[164:167], v[208:211], v[92:95]
	v_mfma_f32_16x16x32_bf16 v[84:87], v[156:159], v[216:219], v[84:87]
	v_mfma_f32_16x16x32_bf16 v[76:79], v[164:167], v[216:219], v[76:79]
	v_mfma_f32_16x16x32_bf16 v[112:115], v[168:171], v[184:187], v[112:115]
	v_mfma_f32_16x16x32_bf16 v[104:107], v[176:179], v[184:187], v[104:107]
	v_mfma_f32_16x16x32_bf16 v[96:99], v[168:171], v[196:199], v[96:99]
	v_mfma_f32_16x16x32_bf16 v[88:91], v[176:179], v[196:199], v[88:91]
	v_mfma_f32_16x16x32_bf16 v[80:83], v[168:171], v[204:207], v[80:83]
	v_mfma_f32_16x16x32_bf16 v[72:75], v[176:179], v[204:207], v[72:75]
	v_mfma_f32_16x16x32_bf16 v[68:71], v[168:171], v[212:215], v[68:71]
	v_mfma_f32_16x16x32_bf16 v[64:67], v[176:179], v[212:215], v[64:67]
	v_mfma_f32_16x16x32_bf16 v[112:115], v[172:175], v[192:195], v[112:115]
	v_mfma_f32_16x16x32_bf16 v[104:107], v[180:183], v[192:195], v[104:107]
	v_mfma_f32_16x16x32_bf16 v[96:99], v[172:175], v[200:203], v[96:99]
	v_mfma_f32_16x16x32_bf16 v[88:91], v[180:183], v[200:203], v[88:91]
	v_mfma_f32_16x16x32_bf16 v[80:83], v[172:175], v[208:211], v[80:83]
	v_mfma_f32_16x16x32_bf16 v[72:75], v[180:183], v[208:211], v[72:75]
	v_mfma_f32_16x16x32_bf16 v[68:71], v[172:175], v[216:219], v[68:71]
	v_mfma_f32_16x16x32_bf16 v[64:67], v[180:183], v[216:219], v[64:67]
	s_barrier
	s_add_i32 s40, s76, s53
	s_mov_b32 m0, s40
	ds_read_b128 v[184:187], v151 offset:49152
	ds_read_b128 v[192:195], v151 offset:50176
	ds_read_b128 v[196:199], v151 offset:51200
	ds_read_b128 v[200:203], v151 offset:52224
	ds_read_b128 v[204:207], v151 offset:53248
	ds_read_b128 v[208:211], v151 offset:54272
	ds_read_b128 v[212:215], v151 offset:55296
	ds_read_b128 v[216:219], v151 offset:56320
	global_load_lds_dwordx4 v130, s[98:99]
	s_add_i32 m0, s40, 0x2000
	s_add_u32 s38, s38, 0x40080
	s_addc_u32 s39, s39, 0
	s_add_i32 s40, s77, s53
	global_load_lds_dwordx4 v134, s[98:99]
	s_mov_b32 m0, s40
	s_nop 0
	global_load_lds_dwordx4 v130, s[38:39]
	s_add_i32 m0, s40, 0x2000
	s_nop 0
	global_load_lds_dwordx4 v134, s[38:39]
	s_mov_b32 m0, s63
	s_nop 0
	global_load_lds_dwordx4 v128, s[100:101]
	s_mov_b32 m0, s64
	s_nop 0
	global_load_lds_dwordx4 v132, s[100:101]
	s_waitcnt vmcnt(8)
	s_waitcnt lgkmcnt(0)
	s_barrier
	v_mfma_f32_16x16x32_bf16 v[60:63], v[152:155], v[184:187], v[60:63]
	v_mfma_f32_16x16x32_bf16 v[56:59], v[160:163], v[184:187], v[56:59]
	v_mfma_f32_16x16x32_bf16 v[52:55], v[152:155], v[196:199], v[52:55]
	v_mfma_f32_16x16x32_bf16 v[44:47], v[160:163], v[196:199], v[44:47]
	v_mfma_f32_16x16x32_bf16 v[36:39], v[152:155], v[204:207], v[36:39]
	v_mfma_f32_16x16x32_bf16 v[28:31], v[160:163], v[204:207], v[28:31]
	v_mfma_f32_16x16x32_bf16 v[20:23], v[152:155], v[212:215], v[20:23]
	v_mfma_f32_16x16x32_bf16 v[12:15], v[160:163], v[212:215], v[12:15]
	v_mfma_f32_16x16x32_bf16 v[60:63], v[156:159], v[192:195], v[60:63]
	v_mfma_f32_16x16x32_bf16 v[56:59], v[164:167], v[192:195], v[56:59]
	v_mfma_f32_16x16x32_bf16 v[52:55], v[156:159], v[200:203], v[52:55]
	v_mfma_f32_16x16x32_bf16 v[44:47], v[164:167], v[200:203], v[44:47]
	v_mfma_f32_16x16x32_bf16 v[36:39], v[156:159], v[208:211], v[36:39]
	v_mfma_f32_16x16x32_bf16 v[28:31], v[164:167], v[208:211], v[28:31]
	v_mfma_f32_16x16x32_bf16 v[20:23], v[156:159], v[216:219], v[20:23]
	v_mfma_f32_16x16x32_bf16 v[12:15], v[164:167], v[216:219], v[12:15]
	v_mfma_f32_16x16x32_bf16 v[48:51], v[168:171], v[184:187], v[48:51]
	v_mfma_f32_16x16x32_bf16 v[40:43], v[176:179], v[184:187], v[40:43]
	v_mfma_f32_16x16x32_bf16 v[32:35], v[168:171], v[196:199], v[32:35]
	v_mfma_f32_16x16x32_bf16 v[24:27], v[176:179], v[196:199], v[24:27]
	v_mfma_f32_16x16x32_bf16 v[16:19], v[168:171], v[204:207], v[16:19]
	v_mfma_f32_16x16x32_bf16 v[8:11], v[176:179], v[204:207], v[8:11]
	v_mfma_f32_16x16x32_bf16 v[4:7], v[168:171], v[212:215], v[4:7]
	v_mfma_f32_16x16x32_bf16 v[0:3], v[176:179], v[212:215], v[0:3]
	v_mfma_f32_16x16x32_bf16 v[48:51], v[172:175], v[192:195], v[48:51]
	v_mfma_f32_16x16x32_bf16 v[40:43], v[180:183], v[192:195], v[40:43]
	v_mfma_f32_16x16x32_bf16 v[32:35], v[172:175], v[200:203], v[32:35]
	v_mfma_f32_16x16x32_bf16 v[24:27], v[180:183], v[200:203], v[24:27]
	v_mfma_f32_16x16x32_bf16 v[16:19], v[172:175], v[208:211], v[16:19]
	v_mfma_f32_16x16x32_bf16 v[8:11], v[180:183], v[208:211], v[8:11]
	v_mfma_f32_16x16x32_bf16 v[4:7], v[172:175], v[216:219], v[4:7]
	v_mfma_f32_16x16x32_bf16 v[0:3], v[180:183], v[216:219], v[0:3]
	s_barrier
	s_add_i32 s75, s75, 2
	s_add_u32 s34, s34, 0x100
	s_addc_u32 s35, s35, 0
	s_add_u32 s73, s73, 0x100
	s_addc_u32 s74, s74, 0
	s_cmp_gt_u32 s75, 13
	s_cbranch_scc0 .LBB0_700

.LBB0_837:
	ds_read_b128 v[152:155], v149
	ds_read_b128 v[156:159], v149 offset:1024
	ds_read_b128 v[160:163], v149 offset:2048
	ds_read_b128 v[164:167], v149 offset:3072
	ds_read_b128 v[168:171], v150
	ds_read_b128 v[172:175], v150 offset:1024
	ds_read_b128 v[176:179], v150 offset:2048
	ds_read_b128 v[180:183], v150 offset:3072
	s_add_u32 s40, s34, 0xfffc0080
	s_addc_u32 s41, s35, -1
	s_cmp_eq_u32 s77, 12
	s_cselect_b32 s43, s25, s41
	s_cselect_b32 s42, s54, s40
	s_cselect_b32 s41, s23, s76
	s_cselect_b32 s40, s55, s75
	s_add_i32 m0, s31, 0xc000
	ds_read_b128 v[184:187], v151
	ds_read_b128 v[192:195], v151 offset:1024
	ds_read_b128 v[196:199], v151 offset:2048
	ds_read_b128 v[200:203], v151 offset:3072
	ds_read_b128 v[204:207], v151 offset:4096
	ds_read_b128 v[208:211], v151 offset:5120
	ds_read_b128 v[212:215], v151 offset:6144
	ds_read_b128 v[216:219], v151 offset:7168
	global_load_lds_dwordx4 v136, s[34:35]
	s_add_i32 m0, s31, 0xe000
	s_nop 0
	global_load_lds_dwordx4 v138, s[34:35]
	s_waitcnt vmcnt(8)
	s_waitcnt lgkmcnt(0)
	s_barrier
	v_mfma_f32_16x16x32_bf16 v[124:127], v[152:155], v[184:187], v[124:127]
	v_mfma_f32_16x16x32_bf16 v[120:123], v[160:163], v[184:187], v[120:123]
	v_mfma_f32_16x16x32_bf16 v[108:111], v[152:155], v[196:199], v[108:111]
	v_mfma_f32_16x16x32_bf16 v[104:107], v[160:163], v[196:199], v[104:107]
	v_mfma_f32_16x16x32_bf16 v[92:95], v[152:155], v[204:207], v[92:95]
	v_mfma_f32_16x16x32_bf16 v[88:91], v[160:163], v[204:207], v[88:91]
	v_mfma_f32_16x16x32_bf16 v[76:79], v[152:155], v[212:215], v[76:79]
	v_mfma_f32_16x16x32_bf16 v[72:75], v[160:163], v[212:215], v[72:75]
	v_mfma_f32_16x16x32_bf16 v[124:127], v[156:159], v[192:195], v[124:127]
	v_mfma_f32_16x16x32_bf16 v[120:123], v[164:167], v[192:195], v[120:123]
	v_mfma_f32_16x16x32_bf16 v[108:111], v[156:159], v[200:203], v[108:111]
	v_mfma_f32_16x16x32_bf16 v[104:107], v[164:167], v[200:203], v[104:107]
	v_mfma_f32_16x16x32_bf16 v[92:95], v[156:159], v[208:211], v[92:95]
	v_mfma_f32_16x16x32_bf16 v[88:91], v[164:167], v[208:211], v[88:91]
	v_mfma_f32_16x16x32_bf16 v[76:79], v[156:159], v[216:219], v[76:79]
	v_mfma_f32_16x16x32_bf16 v[72:75], v[164:167], v[216:219], v[72:75]
	v_mfma_f32_16x16x32_bf16 v[116:119], v[168:171], v[184:187], v[116:119]
	v_mfma_f32_16x16x32_bf16 v[112:115], v[176:179], v[184:187], v[112:115]
	v_mfma_f32_16x16x32_bf16 v[100:103], v[168:171], v[196:199], v[100:103]
	v_mfma_f32_16x16x32_bf16 v[96:99], v[176:179], v[196:199], v[96:99]
	v_mfma_f32_16x16x32_bf16 v[84:87], v[168:171], v[204:207], v[84:87]
	v_mfma_f32_16x16x32_bf16 v[80:83], v[176:179], v[204:207], v[80:83]
	v_mfma_f32_16x16x32_bf16 v[68:71], v[168:171], v[212:215], v[68:71]
	v_mfma_f32_16x16x32_bf16 v[64:67], v[176:179], v[212:215], v[64:67]
	v_mfma_f32_16x16x32_bf16 v[116:119], v[172:175], v[192:195], v[116:119]
	v_mfma_f32_16x16x32_bf16 v[112:115], v[180:183], v[192:195], v[112:115]
	v_mfma_f32_16x16x32_bf16 v[100:103], v[172:175], v[200:203], v[100:103]
	v_mfma_f32_16x16x32_bf16 v[96:99], v[180:183], v[200:203], v[96:99]
	v_mfma_f32_16x16x32_bf16 v[84:87], v[172:175], v[208:211], v[84:87]
	v_mfma_f32_16x16x32_bf16 v[80:83], v[180:183], v[208:211], v[80:83]
	v_mfma_f32_16x16x32_bf16 v[68:71], v[172:175], v[216:219], v[68:71]
	v_mfma_f32_16x16x32_bf16 v[64:67], v[180:183], v[216:219], v[64:67]
	s_barrier
	s_add_i32 s79, s69, s63
	s_add_u32 s98, s40, 0x80
	s_addc_u32 s99, s41, 0
	s_mov_b32 m0, s79
	ds_read_b128 v[184:187], v151 offset:16384
	ds_read_b128 v[192:195], v151 offset:17408
	ds_read_b128 v[196:199], v151 offset:18432
	ds_read_b128 v[200:203], v151 offset:19456
	ds_read_b128 v[204:207], v151 offset:20480
	ds_read_b128 v[208:211], v151 offset:21504
	ds_read_b128 v[212:215], v151 offset:22528
	ds_read_b128 v[216:219], v151 offset:23552
	global_load_lds_dwordx4 v130, s[40:41]
	s_add_i32 m0, s79, 0x2000
	s_add_u32 s80, s40, 0x40000
	s_addc_u32 s81, s41, 0
	s_add_i32 s79, s70, s63
	global_load_lds_dwordx4 v134, s[40:41]
	s_mov_b32 m0, s79
	s_add_u32 s100, s42, 0x80
	s_addc_u32 s101, s43, 0
	global_load_lds_dwordx4 v130, s[80:81]
	s_add_i32 m0, s79, 0x2000
	s_nop 0
	global_load_lds_dwordx4 v134, s[80:81]
	s_mov_b32 m0, s31
	s_nop 0
	global_load_lds_dwordx4 v128, s[42:43]
	s_mov_b32 m0, s64
	s_nop 0
	global_load_lds_dwordx4 v132, s[42:43]
	s_waitcnt vmcnt(8)
	s_waitcnt lgkmcnt(0)
	s_barrier
	v_mfma_f32_16x16x32_bf16 v[60:63], v[152:155], v[184:187], v[60:63]
	v_mfma_f32_16x16x32_bf16 v[56:59], v[160:163], v[184:187], v[56:59]
	v_mfma_f32_16x16x32_bf16 v[44:47], v[152:155], v[196:199], v[44:47]
	v_mfma_f32_16x16x32_bf16 v[40:43], v[160:163], v[196:199], v[40:43]
	v_mfma_f32_16x16x32_bf16 v[28:31], v[152:155], v[204:207], v[28:31]
	v_mfma_f32_16x16x32_bf16 v[24:27], v[160:163], v[204:207], v[24:27]
	v_mfma_f32_16x16x32_bf16 v[12:15], v[152:155], v[212:215], v[12:15]
	v_mfma_f32_16x16x32_bf16 v[8:11], v[160:163], v[212:215], v[8:11]
	v_mfma_f32_16x16x32_bf16 v[60:63], v[156:159], v[192:195], v[60:63]
	v_mfma_f32_16x16x32_bf16 v[56:59], v[164:167], v[192:195], v[56:59]
	v_mfma_f32_16x16x32_bf16 v[44:47], v[156:159], v[200:203], v[44:47]
	v_mfma_f32_16x16x32_bf16 v[40:43], v[164:167], v[200:203], v[40:43]
	v_mfma_f32_16x16x32_bf16 v[28:31], v[156:159], v[208:211], v[28:31]
	v_mfma_f32_16x16x32_bf16 v[24:27], v[164:167], v[208:211], v[24:27]
	v_mfma_f32_16x16x32_bf16 v[12:15], v[156:159], v[216:219], v[12:15]
	v_mfma_f32_16x16x32_bf16 v[8:11], v[164:167], v[216:219], v[8:11]
	v_mfma_f32_16x16x32_bf16 v[52:55], v[168:171], v[184:187], v[52:55]
	v_mfma_f32_16x16x32_bf16 v[48:51], v[176:179], v[184:187], v[48:51]
	v_mfma_f32_16x16x32_bf16 v[36:39], v[168:171], v[196:199], v[36:39]
	v_mfma_f32_16x16x32_bf16 v[32:35], v[176:179], v[196:199], v[32:35]
	v_mfma_f32_16x16x32_bf16 v[20:23], v[168:171], v[204:207], v[20:23]
	v_mfma_f32_16x16x32_bf16 v[16:19], v[176:179], v[204:207], v[16:19]
	v_mfma_f32_16x16x32_bf16 v[4:7], v[168:171], v[212:215], v[4:7]
	v_mfma_f32_16x16x32_bf16 v[0:3], v[176:179], v[212:215], v[0:3]
	v_mfma_f32_16x16x32_bf16 v[52:55], v[172:175], v[192:195], v[52:55]
	v_mfma_f32_16x16x32_bf16 v[48:51], v[180:183], v[192:195], v[48:51]
	v_mfma_f32_16x16x32_bf16 v[36:39], v[172:175], v[200:203], v[36:39]
	v_mfma_f32_16x16x32_bf16 v[32:35], v[180:183], v[200:203], v[32:35]
	v_mfma_f32_16x16x32_bf16 v[20:23], v[172:175], v[208:211], v[20:23]
	v_mfma_f32_16x16x32_bf16 v[16:19], v[180:183], v[208:211], v[16:19]
	v_mfma_f32_16x16x32_bf16 v[4:7], v[172:175], v[216:219], v[4:7]
	v_mfma_f32_16x16x32_bf16 v[0:3], v[180:183], v[216:219], v[0:3]
	s_barrier
	s_add_i32 s79, 0, 0x18000
	s_add_i32 s80, 0, 0x1c000
	v_add_u32_e32 v164, s79, v147
	v_add_u32_e32 v180, s80, v147
	ds_read_b128 v[152:155], v164
	ds_read_b128 v[156:159], v164 offset:1024
	ds_read_b128 v[160:163], v164 offset:2048
	ds_read_b128 v[164:167], v164 offset:3072
	ds_read_b128 v[168:171], v180
	ds_read_b128 v[172:175], v180 offset:1024
	ds_read_b128 v[176:179], v180 offset:2048
	ds_read_b128 v[180:183], v180 offset:3072
	s_add_u32 s42, s42, 0x40000
	s_addc_u32 s43, s43, 0
	s_mov_b32 m0, s65
	ds_read_b128 v[184:187], v151 offset:32768
	ds_read_b128 v[192:195], v151 offset:33792
	ds_read_b128 v[196:199], v151 offset:34816
	ds_read_b128 v[200:203], v151 offset:35840
	ds_read_b128 v[204:207], v151 offset:36864
	ds_read_b128 v[208:211], v151 offset:37888
	ds_read_b128 v[212:215], v151 offset:38912
	ds_read_b128 v[216:219], v151 offset:39936
	global_load_lds_dwordx4 v128, s[42:43]
	s_mov_b32 m0, s66
	s_nop 0
	global_load_lds_dwordx4 v132, s[42:43]
	s_waitcnt vmcnt(8)
	s_waitcnt lgkmcnt(0)
	s_barrier
	v_mfma_f32_16x16x32_bf16 v[124:127], v[152:155], v[184:187], v[124:127]
	v_mfma_f32_16x16x32_bf16 v[120:123], v[160:163], v[184:187], v[120:123]
	v_mfma_f32_16x16x32_bf16 v[108:111], v[152:155], v[196:199], v[108:111]
	v_mfma_f32_16x16x32_bf16 v[104:107], v[160:163], v[196:199], v[104:107]
	v_mfma_f32_16x16x32_bf16 v[92:95], v[152:155], v[204:207], v[92:95]
	v_mfma_f32_16x16x32_bf16 v[88:91], v[160:163], v[204:207], v[88:91]
	v_mfma_f32_16x16x32_bf16 v[76:79], v[152:155], v[212:215], v[76:79]
	v_mfma_f32_16x16x32_bf16 v[72:75], v[160:163], v[212:215], v[72:75]
	v_mfma_f32_16x16x32_bf16 v[124:127], v[156:159], v[192:195], v[124:127]
	v_mfma_f32_16x16x32_bf16 v[120:123], v[164:167], v[192:195], v[120:123]
	v_mfma_f32_16x16x32_bf16 v[108:111], v[156:159], v[200:203], v[108:111]
	v_mfma_f32_16x16x32_bf16 v[104:107], v[164:167], v[200:203], v[104:107]
	v_mfma_f32_16x16x32_bf16 v[92:95], v[156:159], v[208:211], v[92:95]
	v_mfma_f32_16x16x32_bf16 v[88:91], v[164:167], v[208:211], v[88:91]
	v_mfma_f32_16x16x32_bf16 v[76:79], v[156:159], v[216:219], v[76:79]
	v_mfma_f32_16x16x32_bf16 v[72:75], v[164:167], v[216:219], v[72:75]
	v_mfma_f32_16x16x32_bf16 v[116:119], v[168:171], v[184:187], v[116:119]
	v_mfma_f32_16x16x32_bf16 v[112:115], v[176:179], v[184:187], v[112:115]
	v_mfma_f32_16x16x32_bf16 v[100:103], v[168:171], v[196:199], v[100:103]
	v_mfma_f32_16x16x32_bf16 v[96:99], v[176:179], v[196:199], v[96:99]
	v_mfma_f32_16x16x32_bf16 v[84:87], v[168:171], v[204:207], v[84:87]
	v_mfma_f32_16x16x32_bf16 v[80:83], v[176:179], v[204:207], v[80:83]
	v_mfma_f32_16x16x32_bf16 v[68:71], v[168:171], v[212:215], v[68:71]
	v_mfma_f32_16x16x32_bf16 v[64:67], v[176:179], v[212:215], v[64:67]
	v_mfma_f32_16x16x32_bf16 v[116:119], v[172:175], v[192:195], v[116:119]
	v_mfma_f32_16x16x32_bf16 v[112:115], v[180:183], v[192:195], v[112:115]
	v_mfma_f32_16x16x32_bf16 v[100:103], v[172:175], v[200:203], v[100:103]
	v_mfma_f32_16x16x32_bf16 v[96:99], v[180:183], v[200:203], v[96:99]
	v_mfma_f32_16x16x32_bf16 v[84:87], v[172:175], v[208:211], v[84:87]
	v_mfma_f32_16x16x32_bf16 v[80:83], v[180:183], v[208:211], v[80:83]
	v_mfma_f32_16x16x32_bf16 v[68:71], v[172:175], v[216:219], v[68:71]
	v_mfma_f32_16x16x32_bf16 v[64:67], v[180:183], v[216:219], v[64:67]
	s_barrier
	s_add_i32 s42, s79, s63
	s_mov_b32 m0, s42
	ds_read_b128 v[184:187], v151 offset:49152
	ds_read_b128 v[192:195], v151 offset:50176
	ds_read_b128 v[196:199], v151 offset:51200
	ds_read_b128 v[200:203], v151 offset:52224
	ds_read_b128 v[204:207], v151 offset:53248
	ds_read_b128 v[208:211], v151 offset:54272
	ds_read_b128 v[212:215], v151 offset:55296
	ds_read_b128 v[216:219], v151 offset:56320
	global_load_lds_dwordx4 v130, s[98:99]
	s_add_i32 m0, s42, 0x2000
	s_add_u32 s40, s40, 0x40080
	s_addc_u32 s41, s41, 0
	s_add_i32 s42, s80, s63
	global_load_lds_dwordx4 v134, s[98:99]
	s_mov_b32 m0, s42
	s_nop 0
	global_load_lds_dwordx4 v130, s[40:41]
	s_add_i32 m0, s42, 0x2000
	s_nop 0
	global_load_lds_dwordx4 v134, s[40:41]
	s_mov_b32 m0, s52
	s_nop 0
	global_load_lds_dwordx4 v128, s[100:101]
	s_mov_b32 m0, s53
	s_nop 0
	global_load_lds_dwordx4 v132, s[100:101]
	s_waitcnt vmcnt(8)
	s_waitcnt lgkmcnt(0)
	s_barrier
	v_mfma_f32_16x16x32_bf16 v[60:63], v[152:155], v[184:187], v[60:63]
	v_mfma_f32_16x16x32_bf16 v[56:59], v[160:163], v[184:187], v[56:59]
	v_mfma_f32_16x16x32_bf16 v[44:47], v[152:155], v[196:199], v[44:47]
	v_mfma_f32_16x16x32_bf16 v[40:43], v[160:163], v[196:199], v[40:43]
	v_mfma_f32_16x16x32_bf16 v[28:31], v[152:155], v[204:207], v[28:31]
	v_mfma_f32_16x16x32_bf16 v[24:27], v[160:163], v[204:207], v[24:27]
	v_mfma_f32_16x16x32_bf16 v[12:15], v[152:155], v[212:215], v[12:15]
	v_mfma_f32_16x16x32_bf16 v[8:11], v[160:163], v[212:215], v[8:11]
	v_mfma_f32_16x16x32_bf16 v[60:63], v[156:159], v[192:195], v[60:63]
	v_mfma_f32_16x16x32_bf16 v[56:59], v[164:167], v[192:195], v[56:59]
	v_mfma_f32_16x16x32_bf16 v[44:47], v[156:159], v[200:203], v[44:47]
	v_mfma_f32_16x16x32_bf16 v[40:43], v[164:167], v[200:203], v[40:43]
	v_mfma_f32_16x16x32_bf16 v[28:31], v[156:159], v[208:211], v[28:31]
	v_mfma_f32_16x16x32_bf16 v[24:27], v[164:167], v[208:211], v[24:27]
	v_mfma_f32_16x16x32_bf16 v[12:15], v[156:159], v[216:219], v[12:15]
	v_mfma_f32_16x16x32_bf16 v[8:11], v[164:167], v[216:219], v[8:11]
	v_mfma_f32_16x16x32_bf16 v[52:55], v[168:171], v[184:187], v[52:55]
	v_mfma_f32_16x16x32_bf16 v[48:51], v[176:179], v[184:187], v[48:51]
	v_mfma_f32_16x16x32_bf16 v[36:39], v[168:171], v[196:199], v[36:39]
	v_mfma_f32_16x16x32_bf16 v[32:35], v[176:179], v[196:199], v[32:35]
	v_mfma_f32_16x16x32_bf16 v[20:23], v[168:171], v[204:207], v[20:23]
	v_mfma_f32_16x16x32_bf16 v[16:19], v[176:179], v[204:207], v[16:19]
	v_mfma_f32_16x16x32_bf16 v[4:7], v[168:171], v[212:215], v[4:7]
	v_mfma_f32_16x16x32_bf16 v[0:3], v[176:179], v[212:215], v[0:3]
	v_mfma_f32_16x16x32_bf16 v[52:55], v[172:175], v[192:195], v[52:55]
	v_mfma_f32_16x16x32_bf16 v[48:51], v[180:183], v[192:195], v[48:51]
	v_mfma_f32_16x16x32_bf16 v[36:39], v[172:175], v[200:203], v[36:39]
	v_mfma_f32_16x16x32_bf16 v[32:35], v[180:183], v[200:203], v[32:35]
	v_mfma_f32_16x16x32_bf16 v[20:23], v[172:175], v[208:211], v[20:23]
	v_mfma_f32_16x16x32_bf16 v[16:19], v[180:183], v[208:211], v[16:19]
	v_mfma_f32_16x16x32_bf16 v[4:7], v[172:175], v[216:219], v[4:7]
	v_mfma_f32_16x16x32_bf16 v[0:3], v[180:183], v[216:219], v[0:3]
	s_barrier
	s_add_i32 s77, s77, 2
	s_add_u32 s34, s34, 0x100
	s_addc_u32 s35, s35, 0
	s_add_u32 s75, s75, 0x100
	s_addc_u32 s76, s76, 0
	s_cmp_gt_u32 s77, 13
	s_cbranch_scc0 .LBB0_837

.LBB0_916:
	ds_read_b128 v[152:155], v149
	ds_read_b128 v[156:159], v149 offset:1024
	ds_read_b128 v[160:163], v149 offset:2048
	ds_read_b128 v[164:167], v149 offset:3072
	ds_read_b128 v[168:171], v150
	ds_read_b128 v[172:175], v150 offset:1024
	ds_read_b128 v[176:179], v150 offset:2048
	ds_read_b128 v[180:183], v150 offset:3072
	s_add_u32 s40, s34, 0xfff00080
	s_addc_u32 s41, s35, -1
	s_cmp_eq_u32 s77, 60
	s_cselect_b32 s43, s25, s41
	s_cselect_b32 s42, s55, s40
	s_cselect_b32 s41, s23, s76
	s_cselect_b32 s40, s74, s75
	s_add_i32 m0, s31, 0xc000
	ds_read_b128 v[184:187], v151
	ds_read_b128 v[192:195], v151 offset:1024
	ds_read_b128 v[196:199], v151 offset:2048
	ds_read_b128 v[200:203], v151 offset:3072
	ds_read_b128 v[204:207], v151 offset:4096
	ds_read_b128 v[208:211], v151 offset:5120
	ds_read_b128 v[212:215], v151 offset:6144
	ds_read_b128 v[216:219], v151 offset:7168
	global_load_lds_dwordx4 v136, s[34:35]
	s_add_i32 m0, s31, 0xe000
	s_nop 0
	global_load_lds_dwordx4 v138, s[34:35]
	s_waitcnt vmcnt(8)
	s_waitcnt lgkmcnt(0)
	s_barrier
	v_mfma_f32_16x16x32_bf16 v[124:127], v[152:155], v[184:187], v[124:127]
	v_mfma_f32_16x16x32_bf16 v[120:123], v[160:163], v[184:187], v[120:123]
	v_mfma_f32_16x16x32_bf16 v[116:119], v[152:155], v[196:199], v[116:119]
	v_mfma_f32_16x16x32_bf16 v[108:111], v[160:163], v[196:199], v[108:111]
	v_mfma_f32_16x16x32_bf16 v[100:103], v[152:155], v[204:207], v[100:103]
	v_mfma_f32_16x16x32_bf16 v[92:95], v[160:163], v[204:207], v[92:95]
	v_mfma_f32_16x16x32_bf16 v[84:87], v[152:155], v[212:215], v[84:87]
	v_mfma_f32_16x16x32_bf16 v[76:79], v[160:163], v[212:215], v[76:79]
	v_mfma_f32_16x16x32_bf16 v[124:127], v[156:159], v[192:195], v[124:127]
	v_mfma_f32_16x16x32_bf16 v[120:123], v[164:167], v[192:195], v[120:123]
	v_mfma_f32_16x16x32_bf16 v[116:119], v[156:159], v[200:203], v[116:119]
	v_mfma_f32_16x16x32_bf16 v[108:111], v[164:167], v[200:203], v[108:111]
	v_mfma_f32_16x16x32_bf16 v[100:103], v[156:159], v[208:211], v[100:103]
	v_mfma_f32_16x16x32_bf16 v[92:95], v[164:167], v[208:211], v[92:95]
	v_mfma_f32_16x16x32_bf16 v[84:87], v[156:159], v[216:219], v[84:87]
	v_mfma_f32_16x16x32_bf16 v[76:79], v[164:167], v[216:219], v[76:79]
	v_mfma_f32_16x16x32_bf16 v[112:115], v[168:171], v[184:187], v[112:115]
	v_mfma_f32_16x16x32_bf16 v[104:107], v[176:179], v[184:187], v[104:107]
	v_mfma_f32_16x16x32_bf16 v[96:99], v[168:171], v[196:199], v[96:99]
	v_mfma_f32_16x16x32_bf16 v[88:91], v[176:179], v[196:199], v[88:91]
	v_mfma_f32_16x16x32_bf16 v[80:83], v[168:171], v[204:207], v[80:83]
	v_mfma_f32_16x16x32_bf16 v[72:75], v[176:179], v[204:207], v[72:75]
	v_mfma_f32_16x16x32_bf16 v[68:71], v[168:171], v[212:215], v[68:71]
	v_mfma_f32_16x16x32_bf16 v[64:67], v[176:179], v[212:215], v[64:67]
	v_mfma_f32_16x16x32_bf16 v[112:115], v[172:175], v[192:195], v[112:115]
	v_mfma_f32_16x16x32_bf16 v[104:107], v[180:183], v[192:195], v[104:107]
	v_mfma_f32_16x16x32_bf16 v[96:99], v[172:175], v[200:203], v[96:99]
	v_mfma_f32_16x16x32_bf16 v[88:91], v[180:183], v[200:203], v[88:91]
	v_mfma_f32_16x16x32_bf16 v[80:83], v[172:175], v[208:211], v[80:83]
	v_mfma_f32_16x16x32_bf16 v[72:75], v[180:183], v[208:211], v[72:75]
	v_mfma_f32_16x16x32_bf16 v[68:71], v[172:175], v[216:219], v[68:71]
	v_mfma_f32_16x16x32_bf16 v[64:67], v[180:183], v[216:219], v[64:67]
	s_barrier
	s_add_i32 s79, s68, s61
	s_add_u32 s98, s40, 0x80
	s_addc_u32 s99, s41, 0
	s_mov_b32 m0, s79
	ds_read_b128 v[184:187], v151 offset:16384
	ds_read_b128 v[192:195], v151 offset:17408
	ds_read_b128 v[196:199], v151 offset:18432
	ds_read_b128 v[200:203], v151 offset:19456
	ds_read_b128 v[204:207], v151 offset:20480
	ds_read_b128 v[208:211], v151 offset:21504
	ds_read_b128 v[212:215], v151 offset:22528
	ds_read_b128 v[216:219], v151 offset:23552
	global_load_lds_dwordx4 v130, s[40:41]
	s_add_i32 m0, s79, 0x2000
	s_add_u32 s80, s40, 0x100000
	s_addc_u32 s81, s41, 0
	s_add_i32 s79, s69, s61
	global_load_lds_dwordx4 v134, s[40:41]
	s_mov_b32 m0, s79
	s_add_u32 s100, s42, 0x80
	s_addc_u32 s101, s43, 0
	global_load_lds_dwordx4 v130, s[80:81]
	s_add_i32 m0, s79, 0x2000
	s_nop 0
	global_load_lds_dwordx4 v134, s[80:81]
	s_mov_b32 m0, s31
	s_nop 0
	global_load_lds_dwordx4 v128, s[42:43]
	s_mov_b32 m0, s33
	s_nop 0
	global_load_lds_dwordx4 v132, s[42:43]
	s_waitcnt vmcnt(8)
	s_waitcnt lgkmcnt(0)
	s_barrier
	v_mfma_f32_16x16x32_bf16 v[60:63], v[152:155], v[184:187], v[60:63]
	v_mfma_f32_16x16x32_bf16 v[56:59], v[160:163], v[184:187], v[56:59]
	v_mfma_f32_16x16x32_bf16 v[52:55], v[152:155], v[196:199], v[52:55]
	v_mfma_f32_16x16x32_bf16 v[44:47], v[160:163], v[196:199], v[44:47]
	v_mfma_f32_16x16x32_bf16 v[36:39], v[152:155], v[204:207], v[36:39]
	v_mfma_f32_16x16x32_bf16 v[28:31], v[160:163], v[204:207], v[28:31]
	v_mfma_f32_16x16x32_bf16 v[20:23], v[152:155], v[212:215], v[20:23]
	v_mfma_f32_16x16x32_bf16 v[12:15], v[160:163], v[212:215], v[12:15]
	v_mfma_f32_16x16x32_bf16 v[60:63], v[156:159], v[192:195], v[60:63]
	v_mfma_f32_16x16x32_bf16 v[56:59], v[164:167], v[192:195], v[56:59]
	v_mfma_f32_16x16x32_bf16 v[52:55], v[156:159], v[200:203], v[52:55]
	v_mfma_f32_16x16x32_bf16 v[44:47], v[164:167], v[200:203], v[44:47]
	v_mfma_f32_16x16x32_bf16 v[36:39], v[156:159], v[208:211], v[36:39]
	v_mfma_f32_16x16x32_bf16 v[28:31], v[164:167], v[208:211], v[28:31]
	v_mfma_f32_16x16x32_bf16 v[20:23], v[156:159], v[216:219], v[20:23]
	v_mfma_f32_16x16x32_bf16 v[12:15], v[164:167], v[216:219], v[12:15]
	v_mfma_f32_16x16x32_bf16 v[48:51], v[168:171], v[184:187], v[48:51]
	v_mfma_f32_16x16x32_bf16 v[40:43], v[176:179], v[184:187], v[40:43]
	v_mfma_f32_16x16x32_bf16 v[32:35], v[168:171], v[196:199], v[32:35]
	v_mfma_f32_16x16x32_bf16 v[24:27], v[176:179], v[196:199], v[24:27]
	v_mfma_f32_16x16x32_bf16 v[16:19], v[168:171], v[204:207], v[16:19]
	v_mfma_f32_16x16x32_bf16 v[8:11], v[176:179], v[204:207], v[8:11]
	v_mfma_f32_16x16x32_bf16 v[4:7], v[168:171], v[212:215], v[4:7]
	v_mfma_f32_16x16x32_bf16 v[0:3], v[176:179], v[212:215], v[0:3]
	v_mfma_f32_16x16x32_bf16 v[48:51], v[172:175], v[192:195], v[48:51]
	v_mfma_f32_16x16x32_bf16 v[40:43], v[180:183], v[192:195], v[40:43]
	v_mfma_f32_16x16x32_bf16 v[32:35], v[172:175], v[200:203], v[32:35]
	v_mfma_f32_16x16x32_bf16 v[24:27], v[180:183], v[200:203], v[24:27]
	v_mfma_f32_16x16x32_bf16 v[16:19], v[172:175], v[208:211], v[16:19]
	v_mfma_f32_16x16x32_bf16 v[8:11], v[180:183], v[208:211], v[8:11]
	v_mfma_f32_16x16x32_bf16 v[4:7], v[172:175], v[216:219], v[4:7]
	v_mfma_f32_16x16x32_bf16 v[0:3], v[180:183], v[216:219], v[0:3]
	s_barrier
	s_add_i32 s79, 0, 0x18000
	s_add_i32 s80, 0, 0x1c000
	v_add_u32_e32 v164, s79, v147
	v_add_u32_e32 v180, s80, v147
	ds_read_b128 v[152:155], v164
	ds_read_b128 v[156:159], v164 offset:1024
	ds_read_b128 v[160:163], v164 offset:2048
	ds_read_b128 v[164:167], v164 offset:3072
	ds_read_b128 v[168:171], v180
	ds_read_b128 v[172:175], v180 offset:1024
	ds_read_b128 v[176:179], v180 offset:2048
	ds_read_b128 v[180:183], v180 offset:3072
	s_add_u32 s42, s42, 0x100000
	s_addc_u32 s43, s43, 0
	s_mov_b32 m0, s62
	ds_read_b128 v[184:187], v151 offset:32768
	ds_read_b128 v[192:195], v151 offset:33792
	ds_read_b128 v[196:199], v151 offset:34816
	ds_read_b128 v[200:203], v151 offset:35840
	ds_read_b128 v[204:207], v151 offset:36864
	ds_read_b128 v[208:211], v151 offset:37888
	ds_read_b128 v[212:215], v151 offset:38912
	ds_read_b128 v[216:219], v151 offset:39936
	global_load_lds_dwordx4 v128, s[42:43]
	s_mov_b32 m0, s63
	s_nop 0
	global_load_lds_dwordx4 v132, s[42:43]
	s_waitcnt vmcnt(8)
	s_waitcnt lgkmcnt(0)
	s_barrier
	v_mfma_f32_16x16x32_bf16 v[124:127], v[152:155], v[184:187], v[124:127]
	v_mfma_f32_16x16x32_bf16 v[120:123], v[160:163], v[184:187], v[120:123]
	v_mfma_f32_16x16x32_bf16 v[116:119], v[152:155], v[196:199], v[116:119]
	v_mfma_f32_16x16x32_bf16 v[108:111], v[160:163], v[196:199], v[108:111]
	v_mfma_f32_16x16x32_bf16 v[100:103], v[152:155], v[204:207], v[100:103]
	v_mfma_f32_16x16x32_bf16 v[92:95], v[160:163], v[204:207], v[92:95]
	v_mfma_f32_16x16x32_bf16 v[84:87], v[152:155], v[212:215], v[84:87]
	v_mfma_f32_16x16x32_bf16 v[76:79], v[160:163], v[212:215], v[76:79]
	v_mfma_f32_16x16x32_bf16 v[124:127], v[156:159], v[192:195], v[124:127]
	v_mfma_f32_16x16x32_bf16 v[120:123], v[164:167], v[192:195], v[120:123]
	v_mfma_f32_16x16x32_bf16 v[116:119], v[156:159], v[200:203], v[116:119]
	v_mfma_f32_16x16x32_bf16 v[108:111], v[164:167], v[200:203], v[108:111]
	v_mfma_f32_16x16x32_bf16 v[100:103], v[156:159], v[208:211], v[100:103]
	v_mfma_f32_16x16x32_bf16 v[92:95], v[164:167], v[208:211], v[92:95]
	v_mfma_f32_16x16x32_bf16 v[84:87], v[156:159], v[216:219], v[84:87]
	v_mfma_f32_16x16x32_bf16 v[76:79], v[164:167], v[216:219], v[76:79]
	v_mfma_f32_16x16x32_bf16 v[112:115], v[168:171], v[184:187], v[112:115]
	v_mfma_f32_16x16x32_bf16 v[104:107], v[176:179], v[184:187], v[104:107]
	v_mfma_f32_16x16x32_bf16 v[96:99], v[168:171], v[196:199], v[96:99]
	v_mfma_f32_16x16x32_bf16 v[88:91], v[176:179], v[196:199], v[88:91]
	v_mfma_f32_16x16x32_bf16 v[80:83], v[168:171], v[204:207], v[80:83]
	v_mfma_f32_16x16x32_bf16 v[72:75], v[176:179], v[204:207], v[72:75]
	v_mfma_f32_16x16x32_bf16 v[68:71], v[168:171], v[212:215], v[68:71]
	v_mfma_f32_16x16x32_bf16 v[64:67], v[176:179], v[212:215], v[64:67]
	v_mfma_f32_16x16x32_bf16 v[112:115], v[172:175], v[192:195], v[112:115]
	v_mfma_f32_16x16x32_bf16 v[104:107], v[180:183], v[192:195], v[104:107]
	v_mfma_f32_16x16x32_bf16 v[96:99], v[172:175], v[200:203], v[96:99]
	v_mfma_f32_16x16x32_bf16 v[88:91], v[180:183], v[200:203], v[88:91]
	v_mfma_f32_16x16x32_bf16 v[80:83], v[172:175], v[208:211], v[80:83]
	v_mfma_f32_16x16x32_bf16 v[72:75], v[180:183], v[208:211], v[72:75]
	v_mfma_f32_16x16x32_bf16 v[68:71], v[172:175], v[216:219], v[68:71]
	v_mfma_f32_16x16x32_bf16 v[64:67], v[180:183], v[216:219], v[64:67]
	s_barrier
	s_add_i32 s42, s79, s61
	s_mov_b32 m0, s42
	ds_read_b128 v[184:187], v151 offset:49152
	ds_read_b128 v[192:195], v151 offset:50176
	ds_read_b128 v[196:199], v151 offset:51200
	ds_read_b128 v[200:203], v151 offset:52224
	ds_read_b128 v[204:207], v151 offset:53248
	ds_read_b128 v[208:211], v151 offset:54272
	ds_read_b128 v[212:215], v151 offset:55296
	ds_read_b128 v[216:219], v151 offset:56320
	global_load_lds_dwordx4 v130, s[98:99]
	s_add_i32 m0, s42, 0x2000
	s_add_u32 s40, s40, 0x100080
	s_addc_u32 s41, s41, 0
	s_add_i32 s42, s80, s61
	global_load_lds_dwordx4 v134, s[98:99]
	s_mov_b32 m0, s42
	s_nop 0
	global_load_lds_dwordx4 v130, s[40:41]
	s_add_i32 m0, s42, 0x2000
	s_nop 0
	global_load_lds_dwordx4 v134, s[40:41]
	s_mov_b32 m0, s65
	s_nop 0
	global_load_lds_dwordx4 v128, s[100:101]
	s_mov_b32 m0, s66
	s_nop 0
	global_load_lds_dwordx4 v132, s[100:101]
	s_waitcnt vmcnt(8)
	s_waitcnt lgkmcnt(0)
	s_barrier
	v_mfma_f32_16x16x32_bf16 v[60:63], v[152:155], v[184:187], v[60:63]
	v_mfma_f32_16x16x32_bf16 v[56:59], v[160:163], v[184:187], v[56:59]
	v_mfma_f32_16x16x32_bf16 v[52:55], v[152:155], v[196:199], v[52:55]
	v_mfma_f32_16x16x32_bf16 v[44:47], v[160:163], v[196:199], v[44:47]
	v_mfma_f32_16x16x32_bf16 v[36:39], v[152:155], v[204:207], v[36:39]
	v_mfma_f32_16x16x32_bf16 v[28:31], v[160:163], v[204:207], v[28:31]
	v_mfma_f32_16x16x32_bf16 v[20:23], v[152:155], v[212:215], v[20:23]
	v_mfma_f32_16x16x32_bf16 v[12:15], v[160:163], v[212:215], v[12:15]
	v_mfma_f32_16x16x32_bf16 v[60:63], v[156:159], v[192:195], v[60:63]
	v_mfma_f32_16x16x32_bf16 v[56:59], v[164:167], v[192:195], v[56:59]
	v_mfma_f32_16x16x32_bf16 v[52:55], v[156:159], v[200:203], v[52:55]
	v_mfma_f32_16x16x32_bf16 v[44:47], v[164:167], v[200:203], v[44:47]
	v_mfma_f32_16x16x32_bf16 v[36:39], v[156:159], v[208:211], v[36:39]
	v_mfma_f32_16x16x32_bf16 v[28:31], v[164:167], v[208:211], v[28:31]
	v_mfma_f32_16x16x32_bf16 v[20:23], v[156:159], v[216:219], v[20:23]
	v_mfma_f32_16x16x32_bf16 v[12:15], v[164:167], v[216:219], v[12:15]
	v_mfma_f32_16x16x32_bf16 v[48:51], v[168:171], v[184:187], v[48:51]
	v_mfma_f32_16x16x32_bf16 v[40:43], v[176:179], v[184:187], v[40:43]
	v_mfma_f32_16x16x32_bf16 v[32:35], v[168:171], v[196:199], v[32:35]
	v_mfma_f32_16x16x32_bf16 v[24:27], v[176:179], v[196:199], v[24:27]
	v_mfma_f32_16x16x32_bf16 v[16:19], v[168:171], v[204:207], v[16:19]
	v_mfma_f32_16x16x32_bf16 v[8:11], v[176:179], v[204:207], v[8:11]
	v_mfma_f32_16x16x32_bf16 v[4:7], v[168:171], v[212:215], v[4:7]
	v_mfma_f32_16x16x32_bf16 v[0:3], v[176:179], v[212:215], v[0:3]
	v_mfma_f32_16x16x32_bf16 v[48:51], v[172:175], v[192:195], v[48:51]
	v_mfma_f32_16x16x32_bf16 v[40:43], v[180:183], v[192:195], v[40:43]
	v_mfma_f32_16x16x32_bf16 v[32:35], v[172:175], v[200:203], v[32:35]
	v_mfma_f32_16x16x32_bf16 v[24:27], v[180:183], v[200:203], v[24:27]
	v_mfma_f32_16x16x32_bf16 v[16:19], v[172:175], v[208:211], v[16:19]
	v_mfma_f32_16x16x32_bf16 v[8:11], v[180:183], v[208:211], v[8:11]
	v_mfma_f32_16x16x32_bf16 v[4:7], v[172:175], v[216:219], v[4:7]
	v_mfma_f32_16x16x32_bf16 v[0:3], v[180:183], v[216:219], v[0:3]
	s_barrier
	s_add_i32 s77, s77, 2
	s_add_u32 s34, s34, 0x100
	s_addc_u32 s35, s35, 0
	s_add_u32 s75, s75, 0x100
	s_addc_u32 s76, s76, 0
	s_cmp_gt_u32 s77, 61
	s_cbranch_scc0 .LBB0_916

.LBB0_1053:
	ds_read_b128 v[152:155], v149
	ds_read_b128 v[156:159], v149 offset:1024
	ds_read_b128 v[160:163], v149 offset:2048
	ds_read_b128 v[164:167], v149 offset:3072
	ds_read_b128 v[168:171], v150
	ds_read_b128 v[172:175], v150 offset:1024
	ds_read_b128 v[176:179], v150 offset:2048
	ds_read_b128 v[180:183], v150 offset:3072
	s_add_u32 s60, s42, 0xfffc0080
	s_addc_u32 s61, s43, -1
	s_cmp_eq_u32 s82, 12
	s_cselect_b32 s63, s27, s61
	s_cselect_b32 s62, s55, s60
	s_cselect_b32 s61, s25, s81
	s_cselect_b32 s60, s79, s80
	s_add_i32 m0, s35, 0xc000
	ds_read_b128 v[184:187], v151
	ds_read_b128 v[192:195], v151 offset:1024
	ds_read_b128 v[196:199], v151 offset:2048
	ds_read_b128 v[200:203], v151 offset:3072
	ds_read_b128 v[204:207], v151 offset:4096
	ds_read_b128 v[208:211], v151 offset:5120
	ds_read_b128 v[212:215], v151 offset:6144
	ds_read_b128 v[216:219], v151 offset:7168
	global_load_lds_dwordx4 v136, s[42:43]
	s_add_i32 m0, s35, 0xe000
	s_nop 0
	global_load_lds_dwordx4 v138, s[42:43]
	s_waitcnt vmcnt(8)
	s_waitcnt lgkmcnt(0)
	s_barrier
	v_mfma_f32_16x16x32_bf16 v[124:127], v[152:155], v[184:187], v[124:127]
	v_mfma_f32_16x16x32_bf16 v[120:123], v[160:163], v[184:187], v[120:123]
	v_mfma_f32_16x16x32_bf16 v[116:119], v[152:155], v[196:199], v[116:119]
	v_mfma_f32_16x16x32_bf16 v[108:111], v[160:163], v[196:199], v[108:111]
	v_mfma_f32_16x16x32_bf16 v[100:103], v[152:155], v[204:207], v[100:103]
	v_mfma_f32_16x16x32_bf16 v[92:95], v[160:163], v[204:207], v[92:95]
	v_mfma_f32_16x16x32_bf16 v[84:87], v[152:155], v[212:215], v[84:87]
	v_mfma_f32_16x16x32_bf16 v[76:79], v[160:163], v[212:215], v[76:79]
	v_mfma_f32_16x16x32_bf16 v[124:127], v[156:159], v[192:195], v[124:127]
	v_mfma_f32_16x16x32_bf16 v[120:123], v[164:167], v[192:195], v[120:123]
	v_mfma_f32_16x16x32_bf16 v[116:119], v[156:159], v[200:203], v[116:119]
	v_mfma_f32_16x16x32_bf16 v[108:111], v[164:167], v[200:203], v[108:111]
	v_mfma_f32_16x16x32_bf16 v[100:103], v[156:159], v[208:211], v[100:103]
	v_mfma_f32_16x16x32_bf16 v[92:95], v[164:167], v[208:211], v[92:95]
	v_mfma_f32_16x16x32_bf16 v[84:87], v[156:159], v[216:219], v[84:87]
	v_mfma_f32_16x16x32_bf16 v[76:79], v[164:167], v[216:219], v[76:79]
	v_mfma_f32_16x16x32_bf16 v[112:115], v[168:171], v[184:187], v[112:115]
	v_mfma_f32_16x16x32_bf16 v[104:107], v[176:179], v[184:187], v[104:107]
	v_mfma_f32_16x16x32_bf16 v[96:99], v[168:171], v[196:199], v[96:99]
	v_mfma_f32_16x16x32_bf16 v[88:91], v[176:179], v[196:199], v[88:91]
	v_mfma_f32_16x16x32_bf16 v[80:83], v[168:171], v[204:207], v[80:83]
	v_mfma_f32_16x16x32_bf16 v[72:75], v[176:179], v[204:207], v[72:75]
	v_mfma_f32_16x16x32_bf16 v[68:71], v[168:171], v[212:215], v[68:71]
	v_mfma_f32_16x16x32_bf16 v[64:67], v[176:179], v[212:215], v[64:67]
	v_mfma_f32_16x16x32_bf16 v[112:115], v[172:175], v[192:195], v[112:115]
	v_mfma_f32_16x16x32_bf16 v[104:107], v[180:183], v[192:195], v[104:107]
	v_mfma_f32_16x16x32_bf16 v[96:99], v[172:175], v[200:203], v[96:99]
	v_mfma_f32_16x16x32_bf16 v[88:91], v[180:183], v[200:203], v[88:91]
	v_mfma_f32_16x16x32_bf16 v[80:83], v[172:175], v[208:211], v[80:83]
	v_mfma_f32_16x16x32_bf16 v[72:75], v[180:183], v[208:211], v[72:75]
	v_mfma_f32_16x16x32_bf16 v[68:71], v[172:175], v[216:219], v[68:71]
	v_mfma_f32_16x16x32_bf16 v[64:67], v[180:183], v[216:219], v[64:67]
	s_barrier
	s_add_i32 s83, s72, s65
	s_add_u32 s98, s60, 0x80
	s_addc_u32 s99, s61, 0
	s_mov_b32 m0, s83
	ds_read_b128 v[184:187], v151 offset:16384
	ds_read_b128 v[192:195], v151 offset:17408
	ds_read_b128 v[196:199], v151 offset:18432
	ds_read_b128 v[200:203], v151 offset:19456
	ds_read_b128 v[204:207], v151 offset:20480
	ds_read_b128 v[208:211], v151 offset:21504
	ds_read_b128 v[212:215], v151 offset:22528
	ds_read_b128 v[216:219], v151 offset:23552
	global_load_lds_dwordx4 v130, s[60:61]
	s_add_i32 m0, s83, 0x2000
	s_add_u32 s84, s60, 0x40000
	s_addc_u32 s85, s61, 0
	s_add_i32 s83, s73, s65
	global_load_lds_dwordx4 v134, s[60:61]
	s_mov_b32 m0, s83
	s_add_u32 s100, s62, 0x80
	s_addc_u32 s101, s63, 0
	global_load_lds_dwordx4 v130, s[84:85]
	s_add_i32 m0, s83, 0x2000
	s_nop 0
	global_load_lds_dwordx4 v134, s[84:85]
	s_mov_b32 m0, s35
	s_nop 0
	global_load_lds_dwordx4 v128, s[62:63]
	s_mov_b32 m0, s33
	s_nop 0
	global_load_lds_dwordx4 v132, s[62:63]
	s_waitcnt vmcnt(8)
	s_waitcnt lgkmcnt(0)
	s_barrier
	v_mfma_f32_16x16x32_bf16 v[60:63], v[152:155], v[184:187], v[60:63]
	v_mfma_f32_16x16x32_bf16 v[56:59], v[160:163], v[184:187], v[56:59]
	v_mfma_f32_16x16x32_bf16 v[52:55], v[152:155], v[196:199], v[52:55]
	v_mfma_f32_16x16x32_bf16 v[44:47], v[160:163], v[196:199], v[44:47]
	v_mfma_f32_16x16x32_bf16 v[36:39], v[152:155], v[204:207], v[36:39]
	v_mfma_f32_16x16x32_bf16 v[28:31], v[160:163], v[204:207], v[28:31]
	v_mfma_f32_16x16x32_bf16 v[20:23], v[152:155], v[212:215], v[20:23]
	v_mfma_f32_16x16x32_bf16 v[12:15], v[160:163], v[212:215], v[12:15]
	v_mfma_f32_16x16x32_bf16 v[60:63], v[156:159], v[192:195], v[60:63]
	v_mfma_f32_16x16x32_bf16 v[56:59], v[164:167], v[192:195], v[56:59]
	v_mfma_f32_16x16x32_bf16 v[52:55], v[156:159], v[200:203], v[52:55]
	v_mfma_f32_16x16x32_bf16 v[44:47], v[164:167], v[200:203], v[44:47]
	v_mfma_f32_16x16x32_bf16 v[36:39], v[156:159], v[208:211], v[36:39]
	v_mfma_f32_16x16x32_bf16 v[28:31], v[164:167], v[208:211], v[28:31]
	v_mfma_f32_16x16x32_bf16 v[20:23], v[156:159], v[216:219], v[20:23]
	v_mfma_f32_16x16x32_bf16 v[12:15], v[164:167], v[216:219], v[12:15]
	v_mfma_f32_16x16x32_bf16 v[48:51], v[168:171], v[184:187], v[48:51]
	v_mfma_f32_16x16x32_bf16 v[40:43], v[176:179], v[184:187], v[40:43]
	v_mfma_f32_16x16x32_bf16 v[32:35], v[168:171], v[196:199], v[32:35]
	v_mfma_f32_16x16x32_bf16 v[24:27], v[176:179], v[196:199], v[24:27]
	v_mfma_f32_16x16x32_bf16 v[16:19], v[168:171], v[204:207], v[16:19]
	v_mfma_f32_16x16x32_bf16 v[8:11], v[176:179], v[204:207], v[8:11]
	v_mfma_f32_16x16x32_bf16 v[4:7], v[168:171], v[212:215], v[4:7]
	v_mfma_f32_16x16x32_bf16 v[0:3], v[176:179], v[212:215], v[0:3]
	v_mfma_f32_16x16x32_bf16 v[48:51], v[172:175], v[192:195], v[48:51]
	v_mfma_f32_16x16x32_bf16 v[40:43], v[180:183], v[192:195], v[40:43]
	v_mfma_f32_16x16x32_bf16 v[32:35], v[172:175], v[200:203], v[32:35]
	v_mfma_f32_16x16x32_bf16 v[24:27], v[180:183], v[200:203], v[24:27]
	v_mfma_f32_16x16x32_bf16 v[16:19], v[172:175], v[208:211], v[16:19]
	v_mfma_f32_16x16x32_bf16 v[8:11], v[180:183], v[208:211], v[8:11]
	v_mfma_f32_16x16x32_bf16 v[4:7], v[172:175], v[216:219], v[4:7]
	v_mfma_f32_16x16x32_bf16 v[0:3], v[180:183], v[216:219], v[0:3]
	s_barrier
	s_add_i32 s83, 0, 0x18000
	s_add_i32 s84, 0, 0x1c000
	v_add_u32_e32 v164, s83, v147
	v_add_u32_e32 v180, s84, v147
	ds_read_b128 v[152:155], v164
	ds_read_b128 v[156:159], v164 offset:1024
	ds_read_b128 v[160:163], v164 offset:2048
	ds_read_b128 v[164:167], v164 offset:3072
	ds_read_b128 v[168:171], v180
	ds_read_b128 v[172:175], v180 offset:1024
	ds_read_b128 v[176:179], v180 offset:2048
	ds_read_b128 v[180:183], v180 offset:3072
	s_add_u32 s62, s62, 0x40000
	s_addc_u32 s63, s63, 0
	s_mov_b32 m0, s66
	ds_read_b128 v[184:187], v151 offset:32768
	ds_read_b128 v[192:195], v151 offset:33792
	ds_read_b128 v[196:199], v151 offset:34816
	ds_read_b128 v[200:203], v151 offset:35840
	ds_read_b128 v[204:207], v151 offset:36864
	ds_read_b128 v[208:211], v151 offset:37888
	ds_read_b128 v[212:215], v151 offset:38912
	ds_read_b128 v[216:219], v151 offset:39936
	global_load_lds_dwordx4 v128, s[62:63]
	s_mov_b32 m0, s67
	s_nop 0
	global_load_lds_dwordx4 v132, s[62:63]
	s_waitcnt vmcnt(8)
	s_waitcnt lgkmcnt(0)
	s_barrier
	v_mfma_f32_16x16x32_bf16 v[124:127], v[152:155], v[184:187], v[124:127]
	v_mfma_f32_16x16x32_bf16 v[120:123], v[160:163], v[184:187], v[120:123]
	v_mfma_f32_16x16x32_bf16 v[116:119], v[152:155], v[196:199], v[116:119]
	v_mfma_f32_16x16x32_bf16 v[108:111], v[160:163], v[196:199], v[108:111]
	v_mfma_f32_16x16x32_bf16 v[100:103], v[152:155], v[204:207], v[100:103]
	v_mfma_f32_16x16x32_bf16 v[92:95], v[160:163], v[204:207], v[92:95]
	v_mfma_f32_16x16x32_bf16 v[84:87], v[152:155], v[212:215], v[84:87]
	v_mfma_f32_16x16x32_bf16 v[76:79], v[160:163], v[212:215], v[76:79]
	v_mfma_f32_16x16x32_bf16 v[124:127], v[156:159], v[192:195], v[124:127]
	v_mfma_f32_16x16x32_bf16 v[120:123], v[164:167], v[192:195], v[120:123]
	v_mfma_f32_16x16x32_bf16 v[116:119], v[156:159], v[200:203], v[116:119]
	v_mfma_f32_16x16x32_bf16 v[108:111], v[164:167], v[200:203], v[108:111]
	v_mfma_f32_16x16x32_bf16 v[100:103], v[156:159], v[208:211], v[100:103]
	v_mfma_f32_16x16x32_bf16 v[92:95], v[164:167], v[208:211], v[92:95]
	v_mfma_f32_16x16x32_bf16 v[84:87], v[156:159], v[216:219], v[84:87]
	v_mfma_f32_16x16x32_bf16 v[76:79], v[164:167], v[216:219], v[76:79]
	v_mfma_f32_16x16x32_bf16 v[112:115], v[168:171], v[184:187], v[112:115]
	v_mfma_f32_16x16x32_bf16 v[104:107], v[176:179], v[184:187], v[104:107]
	v_mfma_f32_16x16x32_bf16 v[96:99], v[168:171], v[196:199], v[96:99]
	v_mfma_f32_16x16x32_bf16 v[88:91], v[176:179], v[196:199], v[88:91]
	v_mfma_f32_16x16x32_bf16 v[80:83], v[168:171], v[204:207], v[80:83]
	v_mfma_f32_16x16x32_bf16 v[72:75], v[176:179], v[204:207], v[72:75]
	v_mfma_f32_16x16x32_bf16 v[68:71], v[168:171], v[212:215], v[68:71]
	v_mfma_f32_16x16x32_bf16 v[64:67], v[176:179], v[212:215], v[64:67]
	v_mfma_f32_16x16x32_bf16 v[112:115], v[172:175], v[192:195], v[112:115]
	v_mfma_f32_16x16x32_bf16 v[104:107], v[180:183], v[192:195], v[104:107]
	v_mfma_f32_16x16x32_bf16 v[96:99], v[172:175], v[200:203], v[96:99]
	v_mfma_f32_16x16x32_bf16 v[88:91], v[180:183], v[200:203], v[88:91]
	v_mfma_f32_16x16x32_bf16 v[80:83], v[172:175], v[208:211], v[80:83]
	v_mfma_f32_16x16x32_bf16 v[72:75], v[180:183], v[208:211], v[72:75]
	v_mfma_f32_16x16x32_bf16 v[68:71], v[172:175], v[216:219], v[68:71]
	v_mfma_f32_16x16x32_bf16 v[64:67], v[180:183], v[216:219], v[64:67]
	s_barrier
	s_add_i32 s62, s83, s65
	s_mov_b32 m0, s62
	ds_read_b128 v[184:187], v151 offset:49152
	ds_read_b128 v[192:195], v151 offset:50176
	ds_read_b128 v[196:199], v151 offset:51200
	ds_read_b128 v[200:203], v151 offset:52224
	ds_read_b128 v[204:207], v151 offset:53248
	ds_read_b128 v[208:211], v151 offset:54272
	ds_read_b128 v[212:215], v151 offset:55296
	ds_read_b128 v[216:219], v151 offset:56320
	global_load_lds_dwordx4 v130, s[98:99]
	s_add_i32 m0, s62, 0x2000
	s_add_u32 s60, s60, 0x40080
	s_addc_u32 s61, s61, 0
	s_add_i32 s62, s84, s65
	global_load_lds_dwordx4 v134, s[98:99]
	s_mov_b32 m0, s62
	s_nop 0
	global_load_lds_dwordx4 v130, s[60:61]
	s_add_i32 m0, s62, 0x2000
	s_nop 0
	global_load_lds_dwordx4 v134, s[60:61]
	s_mov_b32 m0, s69
	s_nop 0
	global_load_lds_dwordx4 v128, s[100:101]
	s_mov_b32 m0, s70
	s_nop 0
	global_load_lds_dwordx4 v132, s[100:101]
	s_waitcnt vmcnt(8)
	s_waitcnt lgkmcnt(0)
	s_barrier
	v_mfma_f32_16x16x32_bf16 v[60:63], v[152:155], v[184:187], v[60:63]
	v_mfma_f32_16x16x32_bf16 v[56:59], v[160:163], v[184:187], v[56:59]
	v_mfma_f32_16x16x32_bf16 v[52:55], v[152:155], v[196:199], v[52:55]
	v_mfma_f32_16x16x32_bf16 v[44:47], v[160:163], v[196:199], v[44:47]
	v_mfma_f32_16x16x32_bf16 v[36:39], v[152:155], v[204:207], v[36:39]
	v_mfma_f32_16x16x32_bf16 v[28:31], v[160:163], v[204:207], v[28:31]
	v_mfma_f32_16x16x32_bf16 v[20:23], v[152:155], v[212:215], v[20:23]
	v_mfma_f32_16x16x32_bf16 v[12:15], v[160:163], v[212:215], v[12:15]
	v_mfma_f32_16x16x32_bf16 v[60:63], v[156:159], v[192:195], v[60:63]
	v_mfma_f32_16x16x32_bf16 v[56:59], v[164:167], v[192:195], v[56:59]
	v_mfma_f32_16x16x32_bf16 v[52:55], v[156:159], v[200:203], v[52:55]
	v_mfma_f32_16x16x32_bf16 v[44:47], v[164:167], v[200:203], v[44:47]
	v_mfma_f32_16x16x32_bf16 v[36:39], v[156:159], v[208:211], v[36:39]
	v_mfma_f32_16x16x32_bf16 v[28:31], v[164:167], v[208:211], v[28:31]
	v_mfma_f32_16x16x32_bf16 v[20:23], v[156:159], v[216:219], v[20:23]
	v_mfma_f32_16x16x32_bf16 v[12:15], v[164:167], v[216:219], v[12:15]
	v_mfma_f32_16x16x32_bf16 v[48:51], v[168:171], v[184:187], v[48:51]
	v_mfma_f32_16x16x32_bf16 v[40:43], v[176:179], v[184:187], v[40:43]
	v_mfma_f32_16x16x32_bf16 v[32:35], v[168:171], v[196:199], v[32:35]
	v_mfma_f32_16x16x32_bf16 v[24:27], v[176:179], v[196:199], v[24:27]
	v_mfma_f32_16x16x32_bf16 v[16:19], v[168:171], v[204:207], v[16:19]
	v_mfma_f32_16x16x32_bf16 v[8:11], v[176:179], v[204:207], v[8:11]
	v_mfma_f32_16x16x32_bf16 v[4:7], v[168:171], v[212:215], v[4:7]
	v_mfma_f32_16x16x32_bf16 v[0:3], v[176:179], v[212:215], v[0:3]
	v_mfma_f32_16x16x32_bf16 v[48:51], v[172:175], v[192:195], v[48:51]
	v_mfma_f32_16x16x32_bf16 v[40:43], v[180:183], v[192:195], v[40:43]
	v_mfma_f32_16x16x32_bf16 v[32:35], v[172:175], v[200:203], v[32:35]
	v_mfma_f32_16x16x32_bf16 v[24:27], v[180:183], v[200:203], v[24:27]
	v_mfma_f32_16x16x32_bf16 v[16:19], v[172:175], v[208:211], v[16:19]
	v_mfma_f32_16x16x32_bf16 v[8:11], v[180:183], v[208:211], v[8:11]
	v_mfma_f32_16x16x32_bf16 v[4:7], v[172:175], v[216:219], v[4:7]
	v_mfma_f32_16x16x32_bf16 v[0:3], v[180:183], v[216:219], v[0:3]
	s_barrier
	s_add_i32 s82, s82, 2
	s_add_u32 s42, s42, 0x100
	s_addc_u32 s43, s43, 0
	s_add_u32 s80, s80, 0x100
	s_addc_u32 s81, s81, 0
	s_cmp_gt_u32 s82, 13
	s_cbranch_scc0 .LBB0_1053

.LBB0_1266:
	ds_read_b128 v[144:147], v151
	ds_read_b128 v[154:157], v151 offset:1024
	ds_read_b128 v[158:161], v151 offset:2048
	ds_read_b128 v[162:165], v151 offset:3072
	ds_read_b128 v[166:169], v152
	ds_read_b128 v[170:173], v152 offset:1024
	ds_read_b128 v[174:177], v152 offset:2048
	ds_read_b128 v[178:181], v152 offset:3072
	s_add_u32 s18, s16, 0x100
	s_addc_u32 s19, s17, 0
	s_cmp_eq_u32 s67, 2
	s_cselect_b32 s23, s5, s19
	s_cselect_b32 s22, s4, s18
	s_cselect_b32 s21, s15, s66
	s_cselect_b32 s20, s14, s65
	v_lshl_add_u64 v[216:217], s[16:17], 0, v[136:137]
	s_add_i32 m0, s31, 0xc000
	ds_read_b128 v[182:185], v153
	ds_read_b128 v[186:189], v153 offset:1024
	ds_read_b128 v[192:195], v153 offset:2048
	ds_read_b128 v[196:199], v153 offset:3072
	ds_read_b128 v[200:203], v153 offset:4096
	ds_read_b128 v[204:207], v153 offset:5120
	ds_read_b128 v[208:211], v153 offset:6144
	ds_read_b128 v[212:215], v153 offset:7168
	global_load_lds_dwordx4 v[216:217], off
	v_lshl_add_u64 v[216:217], s[16:17], 0, v[138:139]
	s_add_i32 m0, s31, 0xe000
	s_nop 0
	global_load_lds_dwordx4 v[216:217], off
	s_waitcnt vmcnt(8)
	s_waitcnt lgkmcnt(0)
	s_barrier
	v_mfma_f32_16x16x32_bf16 v[124:127], v[144:147], v[182:185], v[124:127]
	v_mfma_f32_16x16x32_bf16 v[120:123], v[158:161], v[182:185], v[120:123]
	v_mfma_f32_16x16x32_bf16 v[116:119], v[144:147], v[192:195], v[116:119]
	v_mfma_f32_16x16x32_bf16 v[108:111], v[158:161], v[192:195], v[108:111]
	v_mfma_f32_16x16x32_bf16 v[100:103], v[144:147], v[200:203], v[100:103]
	v_mfma_f32_16x16x32_bf16 v[92:95], v[158:161], v[200:203], v[92:95]
	v_mfma_f32_16x16x32_bf16 v[84:87], v[144:147], v[208:211], v[84:87]
	v_mfma_f32_16x16x32_bf16 v[76:79], v[158:161], v[208:211], v[76:79]
	v_mfma_f32_16x16x32_bf16 v[124:127], v[154:157], v[186:189], v[124:127]
	v_mfma_f32_16x16x32_bf16 v[120:123], v[162:165], v[186:189], v[120:123]
	v_mfma_f32_16x16x32_bf16 v[116:119], v[154:157], v[196:199], v[116:119]
	v_mfma_f32_16x16x32_bf16 v[108:111], v[162:165], v[196:199], v[108:111]
	v_mfma_f32_16x16x32_bf16 v[100:103], v[154:157], v[204:207], v[100:103]
	v_mfma_f32_16x16x32_bf16 v[92:95], v[162:165], v[204:207], v[92:95]
	v_mfma_f32_16x16x32_bf16 v[84:87], v[154:157], v[212:215], v[84:87]
	v_mfma_f32_16x16x32_bf16 v[76:79], v[162:165], v[212:215], v[76:79]
	v_mfma_f32_16x16x32_bf16 v[112:115], v[166:169], v[182:185], v[112:115]
	v_mfma_f32_16x16x32_bf16 v[104:107], v[174:177], v[182:185], v[104:107]
	v_mfma_f32_16x16x32_bf16 v[96:99], v[166:169], v[192:195], v[96:99]
	v_mfma_f32_16x16x32_bf16 v[88:91], v[174:177], v[192:195], v[88:91]
	v_mfma_f32_16x16x32_bf16 v[80:83], v[166:169], v[200:203], v[80:83]
	v_mfma_f32_16x16x32_bf16 v[72:75], v[174:177], v[200:203], v[72:75]
	v_mfma_f32_16x16x32_bf16 v[68:71], v[166:169], v[208:211], v[68:71]
	v_mfma_f32_16x16x32_bf16 v[64:67], v[174:177], v[208:211], v[64:67]
	v_mfma_f32_16x16x32_bf16 v[112:115], v[170:173], v[186:189], v[112:115]
	v_mfma_f32_16x16x32_bf16 v[104:107], v[178:181], v[186:189], v[104:107]
	v_mfma_f32_16x16x32_bf16 v[96:99], v[170:173], v[196:199], v[96:99]
	v_mfma_f32_16x16x32_bf16 v[88:91], v[178:181], v[196:199], v[88:91]
	v_mfma_f32_16x16x32_bf16 v[80:83], v[170:173], v[204:207], v[80:83]
	v_mfma_f32_16x16x32_bf16 v[72:75], v[178:181], v[204:207], v[72:75]
	v_mfma_f32_16x16x32_bf16 v[68:71], v[170:173], v[212:215], v[68:71]
	v_mfma_f32_16x16x32_bf16 v[64:67], v[178:181], v[212:215], v[64:67]
	s_barrier
	s_add_i32 s16, s60, s28
	s_add_u32 s98, s20, 0x80
	s_addc_u32 s99, s21, 0
	s_mov_b32 m0, s16
	ds_read_b128 v[182:185], v153 offset:16384
	ds_read_b128 v[186:189], v153 offset:17408
	ds_read_b128 v[192:195], v153 offset:18432
	ds_read_b128 v[196:199], v153 offset:19456
	ds_read_b128 v[200:203], v153 offset:20480
	ds_read_b128 v[204:207], v153 offset:21504
	ds_read_b128 v[208:211], v153 offset:22528
	ds_read_b128 v[212:215], v153 offset:23552
	global_load_lds_dwordx4 v132, s[20:21]
	s_add_i32 m0, s16, 0x2000
	s_add_u32 s16, s20, 0x18000
	s_addc_u32 s17, s21, 0
	s_add_i32 s68, s61, s28
	global_load_lds_dwordx4 v128, s[20:21]
	s_mov_b32 m0, s68
	s_add_u32 s100, s22, 0x80
	s_addc_u32 s101, s23, 0
	global_load_lds_dwordx4 v132, s[16:17]
	s_add_i32 m0, s68, 0x2000
	s_nop 0
	global_load_lds_dwordx4 v128, s[16:17]
	s_mov_b32 m0, s31
	s_nop 0
	global_load_lds_dwordx4 v134, s[22:23]
	s_mov_b32 m0, s33
	s_nop 0
	global_load_lds_dwordx4 v130, s[22:23]
	s_waitcnt vmcnt(8)
	s_waitcnt lgkmcnt(0)
	s_barrier
	v_mfma_f32_16x16x32_bf16 v[60:63], v[144:147], v[182:185], v[60:63]
	v_mfma_f32_16x16x32_bf16 v[56:59], v[158:161], v[182:185], v[56:59]
	v_mfma_f32_16x16x32_bf16 v[52:55], v[144:147], v[192:195], v[52:55]
	v_mfma_f32_16x16x32_bf16 v[44:47], v[158:161], v[192:195], v[44:47]
	v_mfma_f32_16x16x32_bf16 v[36:39], v[144:147], v[200:203], v[36:39]
	v_mfma_f32_16x16x32_bf16 v[28:31], v[158:161], v[200:203], v[28:31]
	v_mfma_f32_16x16x32_bf16 v[20:23], v[144:147], v[208:211], v[20:23]
	v_mfma_f32_16x16x32_bf16 v[12:15], v[158:161], v[208:211], v[12:15]
	v_mfma_f32_16x16x32_bf16 v[60:63], v[154:157], v[186:189], v[60:63]
	v_mfma_f32_16x16x32_bf16 v[56:59], v[162:165], v[186:189], v[56:59]
	v_mfma_f32_16x16x32_bf16 v[52:55], v[154:157], v[196:199], v[52:55]
	v_mfma_f32_16x16x32_bf16 v[44:47], v[162:165], v[196:199], v[44:47]
	v_mfma_f32_16x16x32_bf16 v[36:39], v[154:157], v[204:207], v[36:39]
	v_mfma_f32_16x16x32_bf16 v[28:31], v[162:165], v[204:207], v[28:31]
	v_mfma_f32_16x16x32_bf16 v[20:23], v[154:157], v[212:215], v[20:23]
	v_mfma_f32_16x16x32_bf16 v[12:15], v[162:165], v[212:215], v[12:15]
	v_mfma_f32_16x16x32_bf16 v[48:51], v[166:169], v[182:185], v[48:51]
	v_mfma_f32_16x16x32_bf16 v[40:43], v[174:177], v[182:185], v[40:43]
	v_mfma_f32_16x16x32_bf16 v[32:35], v[166:169], v[192:195], v[32:35]
	v_mfma_f32_16x16x32_bf16 v[24:27], v[174:177], v[192:195], v[24:27]
	v_mfma_f32_16x16x32_bf16 v[16:19], v[166:169], v[200:203], v[16:19]
	v_mfma_f32_16x16x32_bf16 v[8:11], v[174:177], v[200:203], v[8:11]
	v_mfma_f32_16x16x32_bf16 v[4:7], v[166:169], v[208:211], v[4:7]
	v_mfma_f32_16x16x32_bf16 v[0:3], v[174:177], v[208:211], v[0:3]
	v_mfma_f32_16x16x32_bf16 v[48:51], v[170:173], v[186:189], v[48:51]
	v_mfma_f32_16x16x32_bf16 v[40:43], v[178:181], v[186:189], v[40:43]
	v_mfma_f32_16x16x32_bf16 v[32:35], v[170:173], v[196:199], v[32:35]
	v_mfma_f32_16x16x32_bf16 v[24:27], v[178:181], v[196:199], v[24:27]
	v_mfma_f32_16x16x32_bf16 v[16:19], v[170:173], v[204:207], v[16:19]
	v_mfma_f32_16x16x32_bf16 v[8:11], v[178:181], v[204:207], v[8:11]
	v_mfma_f32_16x16x32_bf16 v[4:7], v[170:173], v[212:215], v[4:7]
	v_mfma_f32_16x16x32_bf16 v[0:3], v[178:181], v[212:215], v[0:3]
	s_barrier
	s_add_i32 s68, 0, 0x18000
	s_add_i32 s69, 0, 0x1c000
	v_add_u32_e32 v162, s68, v149
	v_add_u32_e32 v178, s69, v149
	ds_read_b128 v[144:147], v162
	ds_read_b128 v[154:157], v162 offset:1024
	ds_read_b128 v[158:161], v162 offset:2048
	ds_read_b128 v[162:165], v162 offset:3072
	ds_read_b128 v[166:169], v178
	ds_read_b128 v[170:173], v178 offset:1024
	ds_read_b128 v[174:177], v178 offset:2048
	ds_read_b128 v[178:181], v178 offset:3072
	s_add_u32 s16, s22, 0x18000
	s_addc_u32 s17, s23, 0
	s_mov_b32 m0, s34
	ds_read_b128 v[182:185], v153 offset:32768
	ds_read_b128 v[186:189], v153 offset:33792
	ds_read_b128 v[192:195], v153 offset:34816
	ds_read_b128 v[196:199], v153 offset:35840
	ds_read_b128 v[200:203], v153 offset:36864
	ds_read_b128 v[204:207], v153 offset:37888
	ds_read_b128 v[208:211], v153 offset:38912
	ds_read_b128 v[212:215], v153 offset:39936
	global_load_lds_dwordx4 v134, s[16:17]
	s_mov_b32 m0, s35
	s_nop 0
	global_load_lds_dwordx4 v130, s[16:17]
	s_waitcnt vmcnt(8)
	s_waitcnt lgkmcnt(0)
	s_barrier
	v_mfma_f32_16x16x32_bf16 v[124:127], v[144:147], v[182:185], v[124:127]
	v_mfma_f32_16x16x32_bf16 v[120:123], v[158:161], v[182:185], v[120:123]
	v_mfma_f32_16x16x32_bf16 v[116:119], v[144:147], v[192:195], v[116:119]
	v_mfma_f32_16x16x32_bf16 v[108:111], v[158:161], v[192:195], v[108:111]
	v_mfma_f32_16x16x32_bf16 v[100:103], v[144:147], v[200:203], v[100:103]
	v_mfma_f32_16x16x32_bf16 v[92:95], v[158:161], v[200:203], v[92:95]
	v_mfma_f32_16x16x32_bf16 v[84:87], v[144:147], v[208:211], v[84:87]
	v_mfma_f32_16x16x32_bf16 v[76:79], v[158:161], v[208:211], v[76:79]
	v_mfma_f32_16x16x32_bf16 v[124:127], v[154:157], v[186:189], v[124:127]
	v_mfma_f32_16x16x32_bf16 v[120:123], v[162:165], v[186:189], v[120:123]
	v_mfma_f32_16x16x32_bf16 v[116:119], v[154:157], v[196:199], v[116:119]
	v_mfma_f32_16x16x32_bf16 v[108:111], v[162:165], v[196:199], v[108:111]
	v_mfma_f32_16x16x32_bf16 v[100:103], v[154:157], v[204:207], v[100:103]
	v_mfma_f32_16x16x32_bf16 v[92:95], v[162:165], v[204:207], v[92:95]
	v_mfma_f32_16x16x32_bf16 v[84:87], v[154:157], v[212:215], v[84:87]
	v_mfma_f32_16x16x32_bf16 v[76:79], v[162:165], v[212:215], v[76:79]
	v_mfma_f32_16x16x32_bf16 v[112:115], v[166:169], v[182:185], v[112:115]
	v_mfma_f32_16x16x32_bf16 v[104:107], v[174:177], v[182:185], v[104:107]
	v_mfma_f32_16x16x32_bf16 v[96:99], v[166:169], v[192:195], v[96:99]
	v_mfma_f32_16x16x32_bf16 v[88:91], v[174:177], v[192:195], v[88:91]
	v_mfma_f32_16x16x32_bf16 v[80:83], v[166:169], v[200:203], v[80:83]
	v_mfma_f32_16x16x32_bf16 v[72:75], v[174:177], v[200:203], v[72:75]
	v_mfma_f32_16x16x32_bf16 v[68:71], v[166:169], v[208:211], v[68:71]
	v_mfma_f32_16x16x32_bf16 v[64:67], v[174:177], v[208:211], v[64:67]
	v_mfma_f32_16x16x32_bf16 v[112:115], v[170:173], v[186:189], v[112:115]
	v_mfma_f32_16x16x32_bf16 v[104:107], v[178:181], v[186:189], v[104:107]
	v_mfma_f32_16x16x32_bf16 v[96:99], v[170:173], v[196:199], v[96:99]
	v_mfma_f32_16x16x32_bf16 v[88:91], v[178:181], v[196:199], v[88:91]
	v_mfma_f32_16x16x32_bf16 v[80:83], v[170:173], v[204:207], v[80:83]
	v_mfma_f32_16x16x32_bf16 v[72:75], v[178:181], v[204:207], v[72:75]
	v_mfma_f32_16x16x32_bf16 v[68:71], v[170:173], v[212:215], v[68:71]
	v_mfma_f32_16x16x32_bf16 v[64:67], v[178:181], v[212:215], v[64:67]
	s_barrier
	s_add_i32 s16, s68, s28
	s_mov_b32 m0, s16
	ds_read_b128 v[182:185], v153 offset:49152
	ds_read_b128 v[186:189], v153 offset:50176
	ds_read_b128 v[192:195], v153 offset:51200
	ds_read_b128 v[196:199], v153 offset:52224
	ds_read_b128 v[200:203], v153 offset:53248
	ds_read_b128 v[204:207], v153 offset:54272
	ds_read_b128 v[208:211], v153 offset:55296
	ds_read_b128 v[212:215], v153 offset:56320
	global_load_lds_dwordx4 v132, s[98:99]
	s_add_i32 m0, s16, 0x2000
	s_add_u32 s16, s20, 0x18080
	s_addc_u32 s17, s21, 0
	s_add_i32 s20, s69, s28
	global_load_lds_dwordx4 v128, s[98:99]
	s_mov_b32 m0, s20
	s_nop 0
	global_load_lds_dwordx4 v132, s[16:17]
	s_add_i32 m0, s20, 0x2000
	s_nop 0
	global_load_lds_dwordx4 v128, s[16:17]
	s_mov_b32 m0, s43
	s_nop 0
	global_load_lds_dwordx4 v134, s[100:101]
	s_mov_b32 m0, s52
	s_nop 0
	global_load_lds_dwordx4 v130, s[100:101]
	s_waitcnt vmcnt(8)
	s_waitcnt lgkmcnt(0)
	s_barrier
	v_mfma_f32_16x16x32_bf16 v[60:63], v[144:147], v[182:185], v[60:63]
	v_mfma_f32_16x16x32_bf16 v[56:59], v[158:161], v[182:185], v[56:59]
	v_mfma_f32_16x16x32_bf16 v[52:55], v[144:147], v[192:195], v[52:55]
	v_mfma_f32_16x16x32_bf16 v[44:47], v[158:161], v[192:195], v[44:47]
	v_mfma_f32_16x16x32_bf16 v[36:39], v[144:147], v[200:203], v[36:39]
	v_mfma_f32_16x16x32_bf16 v[28:31], v[158:161], v[200:203], v[28:31]
	v_mfma_f32_16x16x32_bf16 v[20:23], v[144:147], v[208:211], v[20:23]
	v_mfma_f32_16x16x32_bf16 v[12:15], v[158:161], v[208:211], v[12:15]
	v_mfma_f32_16x16x32_bf16 v[60:63], v[154:157], v[186:189], v[60:63]
	v_mfma_f32_16x16x32_bf16 v[56:59], v[162:165], v[186:189], v[56:59]
	v_mfma_f32_16x16x32_bf16 v[52:55], v[154:157], v[196:199], v[52:55]
	v_mfma_f32_16x16x32_bf16 v[44:47], v[162:165], v[196:199], v[44:47]
	v_mfma_f32_16x16x32_bf16 v[36:39], v[154:157], v[204:207], v[36:39]
	v_mfma_f32_16x16x32_bf16 v[28:31], v[162:165], v[204:207], v[28:31]
	v_mfma_f32_16x16x32_bf16 v[20:23], v[154:157], v[212:215], v[20:23]
	v_mfma_f32_16x16x32_bf16 v[12:15], v[162:165], v[212:215], v[12:15]
	v_mfma_f32_16x16x32_bf16 v[48:51], v[166:169], v[182:185], v[48:51]
	v_mfma_f32_16x16x32_bf16 v[40:43], v[174:177], v[182:185], v[40:43]
	v_mfma_f32_16x16x32_bf16 v[32:35], v[166:169], v[192:195], v[32:35]
	v_mfma_f32_16x16x32_bf16 v[24:27], v[174:177], v[192:195], v[24:27]
	v_mfma_f32_16x16x32_bf16 v[16:19], v[166:169], v[200:203], v[16:19]
	v_mfma_f32_16x16x32_bf16 v[8:11], v[174:177], v[200:203], v[8:11]
	v_mfma_f32_16x16x32_bf16 v[4:7], v[166:169], v[208:211], v[4:7]
	v_mfma_f32_16x16x32_bf16 v[0:3], v[174:177], v[208:211], v[0:3]
	v_mfma_f32_16x16x32_bf16 v[48:51], v[170:173], v[186:189], v[48:51]
	v_mfma_f32_16x16x32_bf16 v[40:43], v[178:181], v[186:189], v[40:43]
	v_mfma_f32_16x16x32_bf16 v[32:35], v[170:173], v[196:199], v[32:35]
	v_mfma_f32_16x16x32_bf16 v[24:27], v[178:181], v[196:199], v[24:27]
	v_mfma_f32_16x16x32_bf16 v[16:19], v[170:173], v[204:207], v[16:19]
	v_mfma_f32_16x16x32_bf16 v[8:11], v[178:181], v[204:207], v[8:11]
	v_mfma_f32_16x16x32_bf16 v[4:7], v[170:173], v[212:215], v[4:7]
	v_mfma_f32_16x16x32_bf16 v[0:3], v[178:181], v[212:215], v[0:3]
	s_barrier
	s_add_i32 s67, s67, 2
	s_add_u32 s65, s65, 0x100
	s_addc_u32 s66, s66, 0
	s_cmp_gt_u32 s67, 3
	s_mov_b64 s[16:17], s[18:19]
	s_cbranch_scc0 .LBB0_1266

.LBB0_1434:
	ds_read_b128 v[152:155], v149
	ds_read_b128 v[156:159], v149 offset:1024
	ds_read_b128 v[160:163], v149 offset:2048
	ds_read_b128 v[164:167], v149 offset:3072
	ds_read_b128 v[168:171], v150
	ds_read_b128 v[172:175], v150 offset:1024
	ds_read_b128 v[176:179], v150 offset:2048
	ds_read_b128 v[180:183], v150 offset:3072
	s_add_u32 s34, s30, 0xfffc0080
	s_addc_u32 s35, s31, -1
	s_cmp_eq_u32 s77, 12
	s_cselect_b32 s43, s23, s35
	s_cselect_b32 s42, s55, s34
	s_cselect_b32 s35, s21, s76
	s_cselect_b32 s34, s74, s75
	s_add_i32 m0, s29, 0xc000
	ds_read_b128 v[184:187], v151
	ds_read_b128 v[192:195], v151 offset:1024
	ds_read_b128 v[196:199], v151 offset:2048
	ds_read_b128 v[200:203], v151 offset:3072
	ds_read_b128 v[204:207], v151 offset:4096
	ds_read_b128 v[208:211], v151 offset:5120
	ds_read_b128 v[212:215], v151 offset:6144
	ds_read_b128 v[216:219], v151 offset:7168
	global_load_lds_dwordx4 v136, s[30:31]
	s_add_i32 m0, s29, 0xe000
	s_nop 0
	global_load_lds_dwordx4 v138, s[30:31]
	s_waitcnt vmcnt(8)
	s_waitcnt lgkmcnt(0)
	s_barrier
	v_mfma_f32_16x16x32_bf16 v[124:127], v[152:155], v[184:187], v[124:127]
	v_mfma_f32_16x16x32_bf16 v[120:123], v[160:163], v[184:187], v[120:123]
	v_mfma_f32_16x16x32_bf16 v[116:119], v[152:155], v[196:199], v[116:119]
	v_mfma_f32_16x16x32_bf16 v[108:111], v[160:163], v[196:199], v[108:111]
	v_mfma_f32_16x16x32_bf16 v[100:103], v[152:155], v[204:207], v[100:103]
	v_mfma_f32_16x16x32_bf16 v[92:95], v[160:163], v[204:207], v[92:95]
	v_mfma_f32_16x16x32_bf16 v[84:87], v[152:155], v[212:215], v[84:87]
	v_mfma_f32_16x16x32_bf16 v[76:79], v[160:163], v[212:215], v[76:79]
	v_mfma_f32_16x16x32_bf16 v[124:127], v[156:159], v[192:195], v[124:127]
	v_mfma_f32_16x16x32_bf16 v[120:123], v[164:167], v[192:195], v[120:123]
	v_mfma_f32_16x16x32_bf16 v[116:119], v[156:159], v[200:203], v[116:119]
	v_mfma_f32_16x16x32_bf16 v[108:111], v[164:167], v[200:203], v[108:111]
	v_mfma_f32_16x16x32_bf16 v[100:103], v[156:159], v[208:211], v[100:103]
	v_mfma_f32_16x16x32_bf16 v[92:95], v[164:167], v[208:211], v[92:95]
	v_mfma_f32_16x16x32_bf16 v[84:87], v[156:159], v[216:219], v[84:87]
	v_mfma_f32_16x16x32_bf16 v[76:79], v[164:167], v[216:219], v[76:79]
	v_mfma_f32_16x16x32_bf16 v[112:115], v[168:171], v[184:187], v[112:115]
	v_mfma_f32_16x16x32_bf16 v[104:107], v[176:179], v[184:187], v[104:107]
	v_mfma_f32_16x16x32_bf16 v[96:99], v[168:171], v[196:199], v[96:99]
	v_mfma_f32_16x16x32_bf16 v[88:91], v[176:179], v[196:199], v[88:91]
	v_mfma_f32_16x16x32_bf16 v[80:83], v[168:171], v[204:207], v[80:83]
	v_mfma_f32_16x16x32_bf16 v[72:75], v[176:179], v[204:207], v[72:75]
	v_mfma_f32_16x16x32_bf16 v[68:71], v[168:171], v[212:215], v[68:71]
	v_mfma_f32_16x16x32_bf16 v[64:67], v[176:179], v[212:215], v[64:67]
	v_mfma_f32_16x16x32_bf16 v[112:115], v[172:175], v[192:195], v[112:115]
	v_mfma_f32_16x16x32_bf16 v[104:107], v[180:183], v[192:195], v[104:107]
	v_mfma_f32_16x16x32_bf16 v[96:99], v[172:175], v[200:203], v[96:99]
	v_mfma_f32_16x16x32_bf16 v[88:91], v[180:183], v[200:203], v[88:91]
	v_mfma_f32_16x16x32_bf16 v[80:83], v[172:175], v[208:211], v[80:83]
	v_mfma_f32_16x16x32_bf16 v[72:75], v[180:183], v[208:211], v[72:75]
	v_mfma_f32_16x16x32_bf16 v[68:71], v[172:175], v[216:219], v[68:71]
	v_mfma_f32_16x16x32_bf16 v[64:67], v[180:183], v[216:219], v[64:67]
	s_barrier
	s_add_i32 s79, s68, s61
	s_add_u32 s98, s34, 0x80
	s_addc_u32 s99, s35, 0
	s_mov_b32 m0, s79
	ds_read_b128 v[184:187], v151 offset:16384
	ds_read_b128 v[192:195], v151 offset:17408
	ds_read_b128 v[196:199], v151 offset:18432
	ds_read_b128 v[200:203], v151 offset:19456
	ds_read_b128 v[204:207], v151 offset:20480
	ds_read_b128 v[208:211], v151 offset:21504
	ds_read_b128 v[212:215], v151 offset:22528
	ds_read_b128 v[216:219], v151 offset:23552
	global_load_lds_dwordx4 v130, s[34:35]
	s_add_i32 m0, s79, 0x2000
	s_add_u32 s80, s34, 0x40000
	s_addc_u32 s81, s35, 0
	s_add_i32 s79, s69, s61
	global_load_lds_dwordx4 v134, s[34:35]
	s_mov_b32 m0, s79
	s_add_u32 s100, s42, 0x80
	s_addc_u32 s101, s43, 0
	global_load_lds_dwordx4 v130, s[80:81]
	s_add_i32 m0, s79, 0x2000
	s_nop 0
	global_load_lds_dwordx4 v134, s[80:81]
	s_mov_b32 m0, s29
	s_nop 0
	global_load_lds_dwordx4 v128, s[42:43]
	s_mov_b32 m0, s33
	s_nop 0
	global_load_lds_dwordx4 v132, s[42:43]
	s_waitcnt vmcnt(8)
	s_waitcnt lgkmcnt(0)
	s_barrier
	v_mfma_f32_16x16x32_bf16 v[60:63], v[152:155], v[184:187], v[60:63]
	v_mfma_f32_16x16x32_bf16 v[56:59], v[160:163], v[184:187], v[56:59]
	v_mfma_f32_16x16x32_bf16 v[52:55], v[152:155], v[196:199], v[52:55]
	v_mfma_f32_16x16x32_bf16 v[44:47], v[160:163], v[196:199], v[44:47]
	v_mfma_f32_16x16x32_bf16 v[36:39], v[152:155], v[204:207], v[36:39]
	v_mfma_f32_16x16x32_bf16 v[28:31], v[160:163], v[204:207], v[28:31]
	v_mfma_f32_16x16x32_bf16 v[20:23], v[152:155], v[212:215], v[20:23]
	v_mfma_f32_16x16x32_bf16 v[12:15], v[160:163], v[212:215], v[12:15]
	v_mfma_f32_16x16x32_bf16 v[60:63], v[156:159], v[192:195], v[60:63]
	v_mfma_f32_16x16x32_bf16 v[56:59], v[164:167], v[192:195], v[56:59]
	v_mfma_f32_16x16x32_bf16 v[52:55], v[156:159], v[200:203], v[52:55]
	v_mfma_f32_16x16x32_bf16 v[44:47], v[164:167], v[200:203], v[44:47]
	v_mfma_f32_16x16x32_bf16 v[36:39], v[156:159], v[208:211], v[36:39]
	v_mfma_f32_16x16x32_bf16 v[28:31], v[164:167], v[208:211], v[28:31]
	v_mfma_f32_16x16x32_bf16 v[20:23], v[156:159], v[216:219], v[20:23]
	v_mfma_f32_16x16x32_bf16 v[12:15], v[164:167], v[216:219], v[12:15]
	v_mfma_f32_16x16x32_bf16 v[48:51], v[168:171], v[184:187], v[48:51]
	v_mfma_f32_16x16x32_bf16 v[40:43], v[176:179], v[184:187], v[40:43]
	v_mfma_f32_16x16x32_bf16 v[32:35], v[168:171], v[196:199], v[32:35]
	v_mfma_f32_16x16x32_bf16 v[24:27], v[176:179], v[196:199], v[24:27]
	v_mfma_f32_16x16x32_bf16 v[16:19], v[168:171], v[204:207], v[16:19]
	v_mfma_f32_16x16x32_bf16 v[8:11], v[176:179], v[204:207], v[8:11]
	v_mfma_f32_16x16x32_bf16 v[4:7], v[168:171], v[212:215], v[4:7]
	v_mfma_f32_16x16x32_bf16 v[0:3], v[176:179], v[212:215], v[0:3]
	v_mfma_f32_16x16x32_bf16 v[48:51], v[172:175], v[192:195], v[48:51]
	v_mfma_f32_16x16x32_bf16 v[40:43], v[180:183], v[192:195], v[40:43]
	v_mfma_f32_16x16x32_bf16 v[32:35], v[172:175], v[200:203], v[32:35]
	v_mfma_f32_16x16x32_bf16 v[24:27], v[180:183], v[200:203], v[24:27]
	v_mfma_f32_16x16x32_bf16 v[16:19], v[172:175], v[208:211], v[16:19]
	v_mfma_f32_16x16x32_bf16 v[8:11], v[180:183], v[208:211], v[8:11]
	v_mfma_f32_16x16x32_bf16 v[4:7], v[172:175], v[216:219], v[4:7]
	v_mfma_f32_16x16x32_bf16 v[0:3], v[180:183], v[216:219], v[0:3]
	s_barrier
	s_add_i32 s79, 0, 0x18000
	s_add_i32 s80, 0, 0x1c000
	v_add_u32_e32 v164, s79, v147
	v_add_u32_e32 v180, s80, v147
	ds_read_b128 v[152:155], v164
	ds_read_b128 v[156:159], v164 offset:1024
	ds_read_b128 v[160:163], v164 offset:2048
	ds_read_b128 v[164:167], v164 offset:3072
	ds_read_b128 v[168:171], v180
	ds_read_b128 v[172:175], v180 offset:1024
	ds_read_b128 v[176:179], v180 offset:2048
	ds_read_b128 v[180:183], v180 offset:3072
	s_add_u32 s42, s42, 0x40000
	s_addc_u32 s43, s43, 0
	s_mov_b32 m0, s62
	ds_read_b128 v[184:187], v151 offset:32768
	ds_read_b128 v[192:195], v151 offset:33792
	ds_read_b128 v[196:199], v151 offset:34816
	ds_read_b128 v[200:203], v151 offset:35840
	ds_read_b128 v[204:207], v151 offset:36864
	ds_read_b128 v[208:211], v151 offset:37888
	ds_read_b128 v[212:215], v151 offset:38912
	ds_read_b128 v[216:219], v151 offset:39936
	global_load_lds_dwordx4 v128, s[42:43]
	s_mov_b32 m0, s63
	s_nop 0
	global_load_lds_dwordx4 v132, s[42:43]
	s_waitcnt vmcnt(8)
	s_waitcnt lgkmcnt(0)
	s_barrier
	v_mfma_f32_16x16x32_bf16 v[124:127], v[152:155], v[184:187], v[124:127]
	v_mfma_f32_16x16x32_bf16 v[120:123], v[160:163], v[184:187], v[120:123]
	v_mfma_f32_16x16x32_bf16 v[116:119], v[152:155], v[196:199], v[116:119]
	v_mfma_f32_16x16x32_bf16 v[108:111], v[160:163], v[196:199], v[108:111]
	v_mfma_f32_16x16x32_bf16 v[100:103], v[152:155], v[204:207], v[100:103]
	v_mfma_f32_16x16x32_bf16 v[92:95], v[160:163], v[204:207], v[92:95]
	v_mfma_f32_16x16x32_bf16 v[84:87], v[152:155], v[212:215], v[84:87]
	v_mfma_f32_16x16x32_bf16 v[76:79], v[160:163], v[212:215], v[76:79]
	v_mfma_f32_16x16x32_bf16 v[124:127], v[156:159], v[192:195], v[124:127]
	v_mfma_f32_16x16x32_bf16 v[120:123], v[164:167], v[192:195], v[120:123]
	v_mfma_f32_16x16x32_bf16 v[116:119], v[156:159], v[200:203], v[116:119]
	v_mfma_f32_16x16x32_bf16 v[108:111], v[164:167], v[200:203], v[108:111]
	v_mfma_f32_16x16x32_bf16 v[100:103], v[156:159], v[208:211], v[100:103]
	v_mfma_f32_16x16x32_bf16 v[92:95], v[164:167], v[208:211], v[92:95]
	v_mfma_f32_16x16x32_bf16 v[84:87], v[156:159], v[216:219], v[84:87]
	v_mfma_f32_16x16x32_bf16 v[76:79], v[164:167], v[216:219], v[76:79]
	v_mfma_f32_16x16x32_bf16 v[112:115], v[168:171], v[184:187], v[112:115]
	v_mfma_f32_16x16x32_bf16 v[104:107], v[176:179], v[184:187], v[104:107]
	v_mfma_f32_16x16x32_bf16 v[96:99], v[168:171], v[196:199], v[96:99]
	v_mfma_f32_16x16x32_bf16 v[88:91], v[176:179], v[196:199], v[88:91]
	v_mfma_f32_16x16x32_bf16 v[80:83], v[168:171], v[204:207], v[80:83]
	v_mfma_f32_16x16x32_bf16 v[72:75], v[176:179], v[204:207], v[72:75]
	v_mfma_f32_16x16x32_bf16 v[68:71], v[168:171], v[212:215], v[68:71]
	v_mfma_f32_16x16x32_bf16 v[64:67], v[176:179], v[212:215], v[64:67]
	v_mfma_f32_16x16x32_bf16 v[112:115], v[172:175], v[192:195], v[112:115]
	v_mfma_f32_16x16x32_bf16 v[104:107], v[180:183], v[192:195], v[104:107]
	v_mfma_f32_16x16x32_bf16 v[96:99], v[172:175], v[200:203], v[96:99]
	v_mfma_f32_16x16x32_bf16 v[88:91], v[180:183], v[200:203], v[88:91]
	v_mfma_f32_16x16x32_bf16 v[80:83], v[172:175], v[208:211], v[80:83]
	v_mfma_f32_16x16x32_bf16 v[72:75], v[180:183], v[208:211], v[72:75]
	v_mfma_f32_16x16x32_bf16 v[68:71], v[172:175], v[216:219], v[68:71]
	v_mfma_f32_16x16x32_bf16 v[64:67], v[180:183], v[216:219], v[64:67]
	s_barrier
	s_add_i32 s42, s79, s61
	s_mov_b32 m0, s42
	ds_read_b128 v[184:187], v151 offset:49152
	ds_read_b128 v[192:195], v151 offset:50176
	ds_read_b128 v[196:199], v151 offset:51200
	ds_read_b128 v[200:203], v151 offset:52224
	ds_read_b128 v[204:207], v151 offset:53248
	ds_read_b128 v[208:211], v151 offset:54272
	ds_read_b128 v[212:215], v151 offset:55296
	ds_read_b128 v[216:219], v151 offset:56320
	global_load_lds_dwordx4 v130, s[98:99]
	s_add_i32 m0, s42, 0x2000
	s_add_u32 s34, s34, 0x40080
	s_addc_u32 s35, s35, 0
	s_add_i32 s42, s80, s61
	global_load_lds_dwordx4 v134, s[98:99]
	s_mov_b32 m0, s42
	s_nop 0
	global_load_lds_dwordx4 v130, s[34:35]
	s_add_i32 m0, s42, 0x2000
	s_nop 0
	global_load_lds_dwordx4 v134, s[34:35]
	s_mov_b32 m0, s65
	s_nop 0
	global_load_lds_dwordx4 v128, s[100:101]
	s_mov_b32 m0, s66
	s_nop 0
	global_load_lds_dwordx4 v132, s[100:101]
	s_waitcnt vmcnt(8)
	s_waitcnt lgkmcnt(0)
	s_barrier
	v_mfma_f32_16x16x32_bf16 v[60:63], v[152:155], v[184:187], v[60:63]
	v_mfma_f32_16x16x32_bf16 v[56:59], v[160:163], v[184:187], v[56:59]
	v_mfma_f32_16x16x32_bf16 v[52:55], v[152:155], v[196:199], v[52:55]
	v_mfma_f32_16x16x32_bf16 v[44:47], v[160:163], v[196:199], v[44:47]
	v_mfma_f32_16x16x32_bf16 v[36:39], v[152:155], v[204:207], v[36:39]
	v_mfma_f32_16x16x32_bf16 v[28:31], v[160:163], v[204:207], v[28:31]
	v_mfma_f32_16x16x32_bf16 v[20:23], v[152:155], v[212:215], v[20:23]
	v_mfma_f32_16x16x32_bf16 v[12:15], v[160:163], v[212:215], v[12:15]
	v_mfma_f32_16x16x32_bf16 v[60:63], v[156:159], v[192:195], v[60:63]
	v_mfma_f32_16x16x32_bf16 v[56:59], v[164:167], v[192:195], v[56:59]
	v_mfma_f32_16x16x32_bf16 v[52:55], v[156:159], v[200:203], v[52:55]
	v_mfma_f32_16x16x32_bf16 v[44:47], v[164:167], v[200:203], v[44:47]
	v_mfma_f32_16x16x32_bf16 v[36:39], v[156:159], v[208:211], v[36:39]
	v_mfma_f32_16x16x32_bf16 v[28:31], v[164:167], v[208:211], v[28:31]
	v_mfma_f32_16x16x32_bf16 v[20:23], v[156:159], v[216:219], v[20:23]
	v_mfma_f32_16x16x32_bf16 v[12:15], v[164:167], v[216:219], v[12:15]
	v_mfma_f32_16x16x32_bf16 v[48:51], v[168:171], v[184:187], v[48:51]
	v_mfma_f32_16x16x32_bf16 v[40:43], v[176:179], v[184:187], v[40:43]
	v_mfma_f32_16x16x32_bf16 v[32:35], v[168:171], v[196:199], v[32:35]
	v_mfma_f32_16x16x32_bf16 v[24:27], v[176:179], v[196:199], v[24:27]
	v_mfma_f32_16x16x32_bf16 v[16:19], v[168:171], v[204:207], v[16:19]
	v_mfma_f32_16x16x32_bf16 v[8:11], v[176:179], v[204:207], v[8:11]
	v_mfma_f32_16x16x32_bf16 v[4:7], v[168:171], v[212:215], v[4:7]
	v_mfma_f32_16x16x32_bf16 v[0:3], v[176:179], v[212:215], v[0:3]
	v_mfma_f32_16x16x32_bf16 v[48:51], v[172:175], v[192:195], v[48:51]
	v_mfma_f32_16x16x32_bf16 v[40:43], v[180:183], v[192:195], v[40:43]
	v_mfma_f32_16x16x32_bf16 v[32:35], v[172:175], v[200:203], v[32:35]
	v_mfma_f32_16x16x32_bf16 v[24:27], v[180:183], v[200:203], v[24:27]
	v_mfma_f32_16x16x32_bf16 v[16:19], v[172:175], v[208:211], v[16:19]
	v_mfma_f32_16x16x32_bf16 v[8:11], v[180:183], v[208:211], v[8:11]
	v_mfma_f32_16x16x32_bf16 v[4:7], v[172:175], v[216:219], v[4:7]
	v_mfma_f32_16x16x32_bf16 v[0:3], v[180:183], v[216:219], v[0:3]
	s_barrier
	s_add_i32 s77, s77, 2
	s_add_u32 s30, s30, 0x100
	s_addc_u32 s31, s31, 0
	s_add_u32 s75, s75, 0x100
	s_addc_u32 s76, s76, 0
	s_cmp_gt_u32 s77, 13
	s_cbranch_scc0 .LBB0_1434

.LBB0_1571:
	ds_read_b128 v[152:155], v149
	ds_read_b128 v[156:159], v149 offset:1024
	ds_read_b128 v[160:163], v149 offset:2048
	ds_read_b128 v[164:167], v149 offset:3072
	ds_read_b128 v[168:171], v150
	ds_read_b128 v[172:175], v150 offset:1024
	ds_read_b128 v[176:179], v150 offset:2048
	ds_read_b128 v[180:183], v150 offset:3072
	s_add_u32 s34, s30, 0xfffc0080
	s_addc_u32 s35, s31, -1
	s_cmp_eq_u32 s77, 12
	s_cselect_b32 s43, s23, s35
	s_cselect_b32 s42, s54, s34
	s_cselect_b32 s35, s21, s76
	s_cselect_b32 s34, s55, s75
	s_add_i32 m0, s29, 0xc000
	ds_read_b128 v[184:187], v151
	ds_read_b128 v[192:195], v151 offset:1024
	ds_read_b128 v[196:199], v151 offset:2048
	ds_read_b128 v[200:203], v151 offset:3072
	ds_read_b128 v[204:207], v151 offset:4096
	ds_read_b128 v[208:211], v151 offset:5120
	ds_read_b128 v[212:215], v151 offset:6144
	ds_read_b128 v[216:219], v151 offset:7168
	global_load_lds_dwordx4 v136, s[30:31]
	s_add_i32 m0, s29, 0xe000
	s_nop 0
	global_load_lds_dwordx4 v138, s[30:31]
	s_waitcnt vmcnt(8)
	s_waitcnt lgkmcnt(0)
	s_barrier
	v_mfma_f32_16x16x32_bf16 v[124:127], v[152:155], v[184:187], v[124:127]
	v_mfma_f32_16x16x32_bf16 v[120:123], v[160:163], v[184:187], v[120:123]
	v_mfma_f32_16x16x32_bf16 v[108:111], v[152:155], v[196:199], v[108:111]
	v_mfma_f32_16x16x32_bf16 v[104:107], v[160:163], v[196:199], v[104:107]
	v_mfma_f32_16x16x32_bf16 v[92:95], v[152:155], v[204:207], v[92:95]
	v_mfma_f32_16x16x32_bf16 v[88:91], v[160:163], v[204:207], v[88:91]
	v_mfma_f32_16x16x32_bf16 v[76:79], v[152:155], v[212:215], v[76:79]
	v_mfma_f32_16x16x32_bf16 v[72:75], v[160:163], v[212:215], v[72:75]
	v_mfma_f32_16x16x32_bf16 v[124:127], v[156:159], v[192:195], v[124:127]
	v_mfma_f32_16x16x32_bf16 v[120:123], v[164:167], v[192:195], v[120:123]
	v_mfma_f32_16x16x32_bf16 v[108:111], v[156:159], v[200:203], v[108:111]
	v_mfma_f32_16x16x32_bf16 v[104:107], v[164:167], v[200:203], v[104:107]
	v_mfma_f32_16x16x32_bf16 v[92:95], v[156:159], v[208:211], v[92:95]
	v_mfma_f32_16x16x32_bf16 v[88:91], v[164:167], v[208:211], v[88:91]
	v_mfma_f32_16x16x32_bf16 v[76:79], v[156:159], v[216:219], v[76:79]
	v_mfma_f32_16x16x32_bf16 v[72:75], v[164:167], v[216:219], v[72:75]
	v_mfma_f32_16x16x32_bf16 v[116:119], v[168:171], v[184:187], v[116:119]
	v_mfma_f32_16x16x32_bf16 v[112:115], v[176:179], v[184:187], v[112:115]
	v_mfma_f32_16x16x32_bf16 v[100:103], v[168:171], v[196:199], v[100:103]
	v_mfma_f32_16x16x32_bf16 v[96:99], v[176:179], v[196:199], v[96:99]
	v_mfma_f32_16x16x32_bf16 v[84:87], v[168:171], v[204:207], v[84:87]
	v_mfma_f32_16x16x32_bf16 v[80:83], v[176:179], v[204:207], v[80:83]
	v_mfma_f32_16x16x32_bf16 v[68:71], v[168:171], v[212:215], v[68:71]
	v_mfma_f32_16x16x32_bf16 v[64:67], v[176:179], v[212:215], v[64:67]
	v_mfma_f32_16x16x32_bf16 v[116:119], v[172:175], v[192:195], v[116:119]
	v_mfma_f32_16x16x32_bf16 v[112:115], v[180:183], v[192:195], v[112:115]
	v_mfma_f32_16x16x32_bf16 v[100:103], v[172:175], v[200:203], v[100:103]
	v_mfma_f32_16x16x32_bf16 v[96:99], v[180:183], v[200:203], v[96:99]
	v_mfma_f32_16x16x32_bf16 v[84:87], v[172:175], v[208:211], v[84:87]
	v_mfma_f32_16x16x32_bf16 v[80:83], v[180:183], v[208:211], v[80:83]
	v_mfma_f32_16x16x32_bf16 v[68:71], v[172:175], v[216:219], v[68:71]
	v_mfma_f32_16x16x32_bf16 v[64:67], v[180:183], v[216:219], v[64:67]
	s_barrier
	s_add_i32 s79, s69, s63
	s_add_u32 s98, s34, 0x80
	s_addc_u32 s99, s35, 0
	s_mov_b32 m0, s79
	ds_read_b128 v[184:187], v151 offset:16384
	ds_read_b128 v[192:195], v151 offset:17408
	ds_read_b128 v[196:199], v151 offset:18432
	ds_read_b128 v[200:203], v151 offset:19456
	ds_read_b128 v[204:207], v151 offset:20480
	ds_read_b128 v[208:211], v151 offset:21504
	ds_read_b128 v[212:215], v151 offset:22528
	ds_read_b128 v[216:219], v151 offset:23552
	global_load_lds_dwordx4 v130, s[34:35]
	s_add_i32 m0, s79, 0x2000
	s_add_u32 s80, s34, 0x40000
	s_addc_u32 s81, s35, 0
	s_add_i32 s79, s70, s63
	global_load_lds_dwordx4 v134, s[34:35]
	s_mov_b32 m0, s79
	s_add_u32 s100, s42, 0x80
	s_addc_u32 s101, s43, 0
	global_load_lds_dwordx4 v130, s[80:81]
	s_add_i32 m0, s79, 0x2000
	s_nop 0
	global_load_lds_dwordx4 v134, s[80:81]
	s_mov_b32 m0, s29
	s_nop 0
	global_load_lds_dwordx4 v128, s[42:43]
	s_mov_b32 m0, s64
	s_nop 0
	global_load_lds_dwordx4 v132, s[42:43]
	s_waitcnt vmcnt(8)
	s_waitcnt lgkmcnt(0)
	s_barrier
	v_mfma_f32_16x16x32_bf16 v[60:63], v[152:155], v[184:187], v[60:63]
	v_mfma_f32_16x16x32_bf16 v[56:59], v[160:163], v[184:187], v[56:59]
	v_mfma_f32_16x16x32_bf16 v[44:47], v[152:155], v[196:199], v[44:47]
	v_mfma_f32_16x16x32_bf16 v[40:43], v[160:163], v[196:199], v[40:43]
	v_mfma_f32_16x16x32_bf16 v[28:31], v[152:155], v[204:207], v[28:31]
	v_mfma_f32_16x16x32_bf16 v[24:27], v[160:163], v[204:207], v[24:27]
	v_mfma_f32_16x16x32_bf16 v[12:15], v[152:155], v[212:215], v[12:15]
	v_mfma_f32_16x16x32_bf16 v[8:11], v[160:163], v[212:215], v[8:11]
	v_mfma_f32_16x16x32_bf16 v[60:63], v[156:159], v[192:195], v[60:63]
	v_mfma_f32_16x16x32_bf16 v[56:59], v[164:167], v[192:195], v[56:59]
	v_mfma_f32_16x16x32_bf16 v[44:47], v[156:159], v[200:203], v[44:47]
	v_mfma_f32_16x16x32_bf16 v[40:43], v[164:167], v[200:203], v[40:43]
	v_mfma_f32_16x16x32_bf16 v[28:31], v[156:159], v[208:211], v[28:31]
	v_mfma_f32_16x16x32_bf16 v[24:27], v[164:167], v[208:211], v[24:27]
	v_mfma_f32_16x16x32_bf16 v[12:15], v[156:159], v[216:219], v[12:15]
	v_mfma_f32_16x16x32_bf16 v[8:11], v[164:167], v[216:219], v[8:11]
	v_mfma_f32_16x16x32_bf16 v[52:55], v[168:171], v[184:187], v[52:55]
	v_mfma_f32_16x16x32_bf16 v[48:51], v[176:179], v[184:187], v[48:51]
	v_mfma_f32_16x16x32_bf16 v[36:39], v[168:171], v[196:199], v[36:39]
	v_mfma_f32_16x16x32_bf16 v[32:35], v[176:179], v[196:199], v[32:35]
	v_mfma_f32_16x16x32_bf16 v[20:23], v[168:171], v[204:207], v[20:23]
	v_mfma_f32_16x16x32_bf16 v[16:19], v[176:179], v[204:207], v[16:19]
	v_mfma_f32_16x16x32_bf16 v[4:7], v[168:171], v[212:215], v[4:7]
	v_mfma_f32_16x16x32_bf16 v[0:3], v[176:179], v[212:215], v[0:3]
	v_mfma_f32_16x16x32_bf16 v[52:55], v[172:175], v[192:195], v[52:55]
	v_mfma_f32_16x16x32_bf16 v[48:51], v[180:183], v[192:195], v[48:51]
	v_mfma_f32_16x16x32_bf16 v[36:39], v[172:175], v[200:203], v[36:39]
	v_mfma_f32_16x16x32_bf16 v[32:35], v[180:183], v[200:203], v[32:35]
	v_mfma_f32_16x16x32_bf16 v[20:23], v[172:175], v[208:211], v[20:23]
	v_mfma_f32_16x16x32_bf16 v[16:19], v[180:183], v[208:211], v[16:19]
	v_mfma_f32_16x16x32_bf16 v[4:7], v[172:175], v[216:219], v[4:7]
	v_mfma_f32_16x16x32_bf16 v[0:3], v[180:183], v[216:219], v[0:3]
	s_barrier
	s_add_i32 s79, 0, 0x18000
	s_add_i32 s80, 0, 0x1c000
	v_add_u32_e32 v164, s79, v147
	v_add_u32_e32 v180, s80, v147
	ds_read_b128 v[152:155], v164
	ds_read_b128 v[156:159], v164 offset:1024
	ds_read_b128 v[160:163], v164 offset:2048
	ds_read_b128 v[164:167], v164 offset:3072
	ds_read_b128 v[168:171], v180
	ds_read_b128 v[172:175], v180 offset:1024
	ds_read_b128 v[176:179], v180 offset:2048
	ds_read_b128 v[180:183], v180 offset:3072
	s_add_u32 s42, s42, 0x40000
	s_addc_u32 s43, s43, 0
	s_mov_b32 m0, s65
	ds_read_b128 v[184:187], v151 offset:32768
	ds_read_b128 v[192:195], v151 offset:33792
	ds_read_b128 v[196:199], v151 offset:34816
	ds_read_b128 v[200:203], v151 offset:35840
	ds_read_b128 v[204:207], v151 offset:36864
	ds_read_b128 v[208:211], v151 offset:37888
	ds_read_b128 v[212:215], v151 offset:38912
	ds_read_b128 v[216:219], v151 offset:39936
	global_load_lds_dwordx4 v128, s[42:43]
	s_mov_b32 m0, s66
	s_nop 0
	global_load_lds_dwordx4 v132, s[42:43]
	s_waitcnt vmcnt(8)
	s_waitcnt lgkmcnt(0)
	s_barrier
	v_mfma_f32_16x16x32_bf16 v[124:127], v[152:155], v[184:187], v[124:127]
	v_mfma_f32_16x16x32_bf16 v[120:123], v[160:163], v[184:187], v[120:123]
	v_mfma_f32_16x16x32_bf16 v[108:111], v[152:155], v[196:199], v[108:111]
	v_mfma_f32_16x16x32_bf16 v[104:107], v[160:163], v[196:199], v[104:107]
	v_mfma_f32_16x16x32_bf16 v[92:95], v[152:155], v[204:207], v[92:95]
	v_mfma_f32_16x16x32_bf16 v[88:91], v[160:163], v[204:207], v[88:91]
	v_mfma_f32_16x16x32_bf16 v[76:79], v[152:155], v[212:215], v[76:79]
	v_mfma_f32_16x16x32_bf16 v[72:75], v[160:163], v[212:215], v[72:75]
	v_mfma_f32_16x16x32_bf16 v[124:127], v[156:159], v[192:195], v[124:127]
	v_mfma_f32_16x16x32_bf16 v[120:123], v[164:167], v[192:195], v[120:123]
	v_mfma_f32_16x16x32_bf16 v[108:111], v[156:159], v[200:203], v[108:111]
	v_mfma_f32_16x16x32_bf16 v[104:107], v[164:167], v[200:203], v[104:107]
	v_mfma_f32_16x16x32_bf16 v[92:95], v[156:159], v[208:211], v[92:95]
	v_mfma_f32_16x16x32_bf16 v[88:91], v[164:167], v[208:211], v[88:91]
	v_mfma_f32_16x16x32_bf16 v[76:79], v[156:159], v[216:219], v[76:79]
	v_mfma_f32_16x16x32_bf16 v[72:75], v[164:167], v[216:219], v[72:75]
	v_mfma_f32_16x16x32_bf16 v[116:119], v[168:171], v[184:187], v[116:119]
	v_mfma_f32_16x16x32_bf16 v[112:115], v[176:179], v[184:187], v[112:115]
	v_mfma_f32_16x16x32_bf16 v[100:103], v[168:171], v[196:199], v[100:103]
	v_mfma_f32_16x16x32_bf16 v[96:99], v[176:179], v[196:199], v[96:99]
	v_mfma_f32_16x16x32_bf16 v[84:87], v[168:171], v[204:207], v[84:87]
	v_mfma_f32_16x16x32_bf16 v[80:83], v[176:179], v[204:207], v[80:83]
	v_mfma_f32_16x16x32_bf16 v[68:71], v[168:171], v[212:215], v[68:71]
	v_mfma_f32_16x16x32_bf16 v[64:67], v[176:179], v[212:215], v[64:67]
	v_mfma_f32_16x16x32_bf16 v[116:119], v[172:175], v[192:195], v[116:119]
	v_mfma_f32_16x16x32_bf16 v[112:115], v[180:183], v[192:195], v[112:115]
	v_mfma_f32_16x16x32_bf16 v[100:103], v[172:175], v[200:203], v[100:103]
	v_mfma_f32_16x16x32_bf16 v[96:99], v[180:183], v[200:203], v[96:99]
	v_mfma_f32_16x16x32_bf16 v[84:87], v[172:175], v[208:211], v[84:87]
	v_mfma_f32_16x16x32_bf16 v[80:83], v[180:183], v[208:211], v[80:83]
	v_mfma_f32_16x16x32_bf16 v[68:71], v[172:175], v[216:219], v[68:71]
	v_mfma_f32_16x16x32_bf16 v[64:67], v[180:183], v[216:219], v[64:67]
	s_barrier
	s_add_i32 s42, s79, s63
	s_mov_b32 m0, s42
	ds_read_b128 v[184:187], v151 offset:49152
	ds_read_b128 v[192:195], v151 offset:50176
	ds_read_b128 v[196:199], v151 offset:51200
	ds_read_b128 v[200:203], v151 offset:52224
	ds_read_b128 v[204:207], v151 offset:53248
	ds_read_b128 v[208:211], v151 offset:54272
	ds_read_b128 v[212:215], v151 offset:55296
	ds_read_b128 v[216:219], v151 offset:56320
	global_load_lds_dwordx4 v130, s[98:99]
	s_add_i32 m0, s42, 0x2000
	s_add_u32 s34, s34, 0x40080
	s_addc_u32 s35, s35, 0
	s_add_i32 s42, s80, s63
	global_load_lds_dwordx4 v134, s[98:99]
	s_mov_b32 m0, s42
	s_nop 0
	global_load_lds_dwordx4 v130, s[34:35]
	s_add_i32 m0, s42, 0x2000
	s_nop 0
	global_load_lds_dwordx4 v134, s[34:35]
	s_mov_b32 m0, s52
	s_nop 0
	global_load_lds_dwordx4 v128, s[100:101]
	s_mov_b32 m0, s53
	s_nop 0
	global_load_lds_dwordx4 v132, s[100:101]
	s_waitcnt vmcnt(8)
	s_waitcnt lgkmcnt(0)
	s_barrier
	v_mfma_f32_16x16x32_bf16 v[60:63], v[152:155], v[184:187], v[60:63]
	v_mfma_f32_16x16x32_bf16 v[56:59], v[160:163], v[184:187], v[56:59]
	v_mfma_f32_16x16x32_bf16 v[44:47], v[152:155], v[196:199], v[44:47]
	v_mfma_f32_16x16x32_bf16 v[40:43], v[160:163], v[196:199], v[40:43]
	v_mfma_f32_16x16x32_bf16 v[28:31], v[152:155], v[204:207], v[28:31]
	v_mfma_f32_16x16x32_bf16 v[24:27], v[160:163], v[204:207], v[24:27]
	v_mfma_f32_16x16x32_bf16 v[12:15], v[152:155], v[212:215], v[12:15]
	v_mfma_f32_16x16x32_bf16 v[8:11], v[160:163], v[212:215], v[8:11]
	v_mfma_f32_16x16x32_bf16 v[60:63], v[156:159], v[192:195], v[60:63]
	v_mfma_f32_16x16x32_bf16 v[56:59], v[164:167], v[192:195], v[56:59]
	v_mfma_f32_16x16x32_bf16 v[44:47], v[156:159], v[200:203], v[44:47]
	v_mfma_f32_16x16x32_bf16 v[40:43], v[164:167], v[200:203], v[40:43]
	v_mfma_f32_16x16x32_bf16 v[28:31], v[156:159], v[208:211], v[28:31]
	v_mfma_f32_16x16x32_bf16 v[24:27], v[164:167], v[208:211], v[24:27]
	v_mfma_f32_16x16x32_bf16 v[12:15], v[156:159], v[216:219], v[12:15]
	v_mfma_f32_16x16x32_bf16 v[8:11], v[164:167], v[216:219], v[8:11]
	v_mfma_f32_16x16x32_bf16 v[52:55], v[168:171], v[184:187], v[52:55]
	v_mfma_f32_16x16x32_bf16 v[48:51], v[176:179], v[184:187], v[48:51]
	v_mfma_f32_16x16x32_bf16 v[36:39], v[168:171], v[196:199], v[36:39]
	v_mfma_f32_16x16x32_bf16 v[32:35], v[176:179], v[196:199], v[32:35]
	v_mfma_f32_16x16x32_bf16 v[20:23], v[168:171], v[204:207], v[20:23]
	v_mfma_f32_16x16x32_bf16 v[16:19], v[176:179], v[204:207], v[16:19]
	v_mfma_f32_16x16x32_bf16 v[4:7], v[168:171], v[212:215], v[4:7]
	v_mfma_f32_16x16x32_bf16 v[0:3], v[176:179], v[212:215], v[0:3]
	v_mfma_f32_16x16x32_bf16 v[52:55], v[172:175], v[192:195], v[52:55]
	v_mfma_f32_16x16x32_bf16 v[48:51], v[180:183], v[192:195], v[48:51]
	v_mfma_f32_16x16x32_bf16 v[36:39], v[172:175], v[200:203], v[36:39]
	v_mfma_f32_16x16x32_bf16 v[32:35], v[180:183], v[200:203], v[32:35]
	v_mfma_f32_16x16x32_bf16 v[20:23], v[172:175], v[208:211], v[20:23]
	v_mfma_f32_16x16x32_bf16 v[16:19], v[180:183], v[208:211], v[16:19]
	v_mfma_f32_16x16x32_bf16 v[4:7], v[172:175], v[216:219], v[4:7]
	v_mfma_f32_16x16x32_bf16 v[0:3], v[180:183], v[216:219], v[0:3]
	s_barrier
	s_add_i32 s77, s77, 2
	s_add_u32 s30, s30, 0x100
	s_addc_u32 s31, s31, 0
	s_add_u32 s75, s75, 0x100
	s_addc_u32 s76, s76, 0
	s_cmp_gt_u32 s77, 13
	s_cbranch_scc0 .LBB0_1571

.LBB0_1650:
	ds_read_b128 v[152:155], v149
	ds_read_b128 v[156:159], v149 offset:1024
	ds_read_b128 v[160:163], v149 offset:2048
	ds_read_b128 v[164:167], v149 offset:3072
	ds_read_b128 v[168:171], v150
	ds_read_b128 v[172:175], v150 offset:1024
	ds_read_b128 v[176:179], v150 offset:2048
	ds_read_b128 v[180:183], v150 offset:3072
	s_add_u32 s34, s30, 0xfff00080
	s_addc_u32 s35, s31, -1
	s_cmp_eq_u32 s75, 60
	s_cselect_b32 s43, s23, s35
	s_cselect_b32 s42, s55, s34
	s_cselect_b32 s35, s21, s74
	s_cselect_b32 s34, s72, s73
	s_add_i32 m0, s29, 0xc000
	ds_read_b128 v[184:187], v151
	ds_read_b128 v[192:195], v151 offset:1024
	ds_read_b128 v[196:199], v151 offset:2048
	ds_read_b128 v[200:203], v151 offset:3072
	ds_read_b128 v[204:207], v151 offset:4096
	ds_read_b128 v[208:211], v151 offset:5120
	ds_read_b128 v[212:215], v151 offset:6144
	ds_read_b128 v[216:219], v151 offset:7168
	global_load_lds_dwordx4 v136, s[30:31]
	s_add_i32 m0, s29, 0xe000
	s_nop 0
	global_load_lds_dwordx4 v138, s[30:31]
	s_waitcnt vmcnt(8)
	s_waitcnt lgkmcnt(0)
	s_barrier
	v_mfma_f32_16x16x32_bf16 v[124:127], v[152:155], v[184:187], v[124:127]
	v_mfma_f32_16x16x32_bf16 v[120:123], v[160:163], v[184:187], v[120:123]
	v_mfma_f32_16x16x32_bf16 v[116:119], v[152:155], v[196:199], v[116:119]
	v_mfma_f32_16x16x32_bf16 v[108:111], v[160:163], v[196:199], v[108:111]
	v_mfma_f32_16x16x32_bf16 v[100:103], v[152:155], v[204:207], v[100:103]
	v_mfma_f32_16x16x32_bf16 v[92:95], v[160:163], v[204:207], v[92:95]
	v_mfma_f32_16x16x32_bf16 v[84:87], v[152:155], v[212:215], v[84:87]
	v_mfma_f32_16x16x32_bf16 v[76:79], v[160:163], v[212:215], v[76:79]
	v_mfma_f32_16x16x32_bf16 v[124:127], v[156:159], v[192:195], v[124:127]
	v_mfma_f32_16x16x32_bf16 v[120:123], v[164:167], v[192:195], v[120:123]
	v_mfma_f32_16x16x32_bf16 v[116:119], v[156:159], v[200:203], v[116:119]
	v_mfma_f32_16x16x32_bf16 v[108:111], v[164:167], v[200:203], v[108:111]
	v_mfma_f32_16x16x32_bf16 v[100:103], v[156:159], v[208:211], v[100:103]
	v_mfma_f32_16x16x32_bf16 v[92:95], v[164:167], v[208:211], v[92:95]
	v_mfma_f32_16x16x32_bf16 v[84:87], v[156:159], v[216:219], v[84:87]
	v_mfma_f32_16x16x32_bf16 v[76:79], v[164:167], v[216:219], v[76:79]
	v_mfma_f32_16x16x32_bf16 v[112:115], v[168:171], v[184:187], v[112:115]
	v_mfma_f32_16x16x32_bf16 v[104:107], v[176:179], v[184:187], v[104:107]
	v_mfma_f32_16x16x32_bf16 v[96:99], v[168:171], v[196:199], v[96:99]
	v_mfma_f32_16x16x32_bf16 v[88:91], v[176:179], v[196:199], v[88:91]
	v_mfma_f32_16x16x32_bf16 v[80:83], v[168:171], v[204:207], v[80:83]
	v_mfma_f32_16x16x32_bf16 v[72:75], v[176:179], v[204:207], v[72:75]
	v_mfma_f32_16x16x32_bf16 v[68:71], v[168:171], v[212:215], v[68:71]
	v_mfma_f32_16x16x32_bf16 v[64:67], v[176:179], v[212:215], v[64:67]
	v_mfma_f32_16x16x32_bf16 v[112:115], v[172:175], v[192:195], v[112:115]
	v_mfma_f32_16x16x32_bf16 v[104:107], v[180:183], v[192:195], v[104:107]
	v_mfma_f32_16x16x32_bf16 v[96:99], v[172:175], v[200:203], v[96:99]
	v_mfma_f32_16x16x32_bf16 v[88:91], v[180:183], v[200:203], v[88:91]
	v_mfma_f32_16x16x32_bf16 v[80:83], v[172:175], v[208:211], v[80:83]
	v_mfma_f32_16x16x32_bf16 v[72:75], v[180:183], v[208:211], v[72:75]
	v_mfma_f32_16x16x32_bf16 v[68:71], v[172:175], v[216:219], v[68:71]
	v_mfma_f32_16x16x32_bf16 v[64:67], v[180:183], v[216:219], v[64:67]
	s_barrier
	s_add_i32 s76, s66, s59
	s_add_u32 s98, s34, 0x80
	s_addc_u32 s99, s35, 0
	s_mov_b32 m0, s76
	ds_read_b128 v[184:187], v151 offset:16384
	ds_read_b128 v[192:195], v151 offset:17408
	ds_read_b128 v[196:199], v151 offset:18432
	ds_read_b128 v[200:203], v151 offset:19456
	ds_read_b128 v[204:207], v151 offset:20480
	ds_read_b128 v[208:211], v151 offset:21504
	ds_read_b128 v[212:215], v151 offset:22528
	ds_read_b128 v[216:219], v151 offset:23552
	global_load_lds_dwordx4 v130, s[34:35]
	s_add_i32 m0, s76, 0x2000
	s_add_u32 s76, s34, 0x100000
	s_addc_u32 s77, s35, 0
	s_add_i32 s79, s67, s59
	global_load_lds_dwordx4 v134, s[34:35]
	s_mov_b32 m0, s79
	s_add_u32 s100, s42, 0x80
	s_addc_u32 s101, s43, 0
	global_load_lds_dwordx4 v130, s[76:77]
	s_add_i32 m0, s79, 0x2000
	s_nop 0
	global_load_lds_dwordx4 v134, s[76:77]
	s_mov_b32 m0, s29
	s_nop 0
	global_load_lds_dwordx4 v128, s[42:43]
	s_mov_b32 m0, s33
	s_nop 0
	global_load_lds_dwordx4 v132, s[42:43]
	s_waitcnt vmcnt(8)
	s_waitcnt lgkmcnt(0)
	s_barrier
	v_mfma_f32_16x16x32_bf16 v[60:63], v[152:155], v[184:187], v[60:63]
	v_mfma_f32_16x16x32_bf16 v[56:59], v[160:163], v[184:187], v[56:59]
	v_mfma_f32_16x16x32_bf16 v[52:55], v[152:155], v[196:199], v[52:55]
	v_mfma_f32_16x16x32_bf16 v[44:47], v[160:163], v[196:199], v[44:47]
	v_mfma_f32_16x16x32_bf16 v[36:39], v[152:155], v[204:207], v[36:39]
	v_mfma_f32_16x16x32_bf16 v[28:31], v[160:163], v[204:207], v[28:31]
	v_mfma_f32_16x16x32_bf16 v[20:23], v[152:155], v[212:215], v[20:23]
	v_mfma_f32_16x16x32_bf16 v[12:15], v[160:163], v[212:215], v[12:15]
	v_mfma_f32_16x16x32_bf16 v[60:63], v[156:159], v[192:195], v[60:63]
	v_mfma_f32_16x16x32_bf16 v[56:59], v[164:167], v[192:195], v[56:59]
	v_mfma_f32_16x16x32_bf16 v[52:55], v[156:159], v[200:203], v[52:55]
	v_mfma_f32_16x16x32_bf16 v[44:47], v[164:167], v[200:203], v[44:47]
	v_mfma_f32_16x16x32_bf16 v[36:39], v[156:159], v[208:211], v[36:39]
	v_mfma_f32_16x16x32_bf16 v[28:31], v[164:167], v[208:211], v[28:31]
	v_mfma_f32_16x16x32_bf16 v[20:23], v[156:159], v[216:219], v[20:23]
	v_mfma_f32_16x16x32_bf16 v[12:15], v[164:167], v[216:219], v[12:15]
	v_mfma_f32_16x16x32_bf16 v[48:51], v[168:171], v[184:187], v[48:51]
	v_mfma_f32_16x16x32_bf16 v[40:43], v[176:179], v[184:187], v[40:43]
	v_mfma_f32_16x16x32_bf16 v[32:35], v[168:171], v[196:199], v[32:35]
	v_mfma_f32_16x16x32_bf16 v[24:27], v[176:179], v[196:199], v[24:27]
	v_mfma_f32_16x16x32_bf16 v[16:19], v[168:171], v[204:207], v[16:19]
	v_mfma_f32_16x16x32_bf16 v[8:11], v[176:179], v[204:207], v[8:11]
	v_mfma_f32_16x16x32_bf16 v[4:7], v[168:171], v[212:215], v[4:7]
	v_mfma_f32_16x16x32_bf16 v[0:3], v[176:179], v[212:215], v[0:3]
	v_mfma_f32_16x16x32_bf16 v[48:51], v[172:175], v[192:195], v[48:51]
	v_mfma_f32_16x16x32_bf16 v[40:43], v[180:183], v[192:195], v[40:43]
	v_mfma_f32_16x16x32_bf16 v[32:35], v[172:175], v[200:203], v[32:35]
	v_mfma_f32_16x16x32_bf16 v[24:27], v[180:183], v[200:203], v[24:27]
	v_mfma_f32_16x16x32_bf16 v[16:19], v[172:175], v[208:211], v[16:19]
	v_mfma_f32_16x16x32_bf16 v[8:11], v[180:183], v[208:211], v[8:11]
	v_mfma_f32_16x16x32_bf16 v[4:7], v[172:175], v[216:219], v[4:7]
	v_mfma_f32_16x16x32_bf16 v[0:3], v[180:183], v[216:219], v[0:3]
	s_barrier
	s_add_i32 s76, 0, 0x18000
	s_add_i32 s77, 0, 0x1c000
	v_add_u32_e32 v164, s76, v147
	v_add_u32_e32 v180, s77, v147
	ds_read_b128 v[152:155], v164
	ds_read_b128 v[156:159], v164 offset:1024
	ds_read_b128 v[160:163], v164 offset:2048
	ds_read_b128 v[164:167], v164 offset:3072
	ds_read_b128 v[168:171], v180
	ds_read_b128 v[172:175], v180 offset:1024
	ds_read_b128 v[176:179], v180 offset:2048
	ds_read_b128 v[180:183], v180 offset:3072
	s_add_u32 s42, s42, 0x100000
	s_addc_u32 s43, s43, 0
	s_mov_b32 m0, s60
	ds_read_b128 v[184:187], v151 offset:32768
	ds_read_b128 v[192:195], v151 offset:33792
	ds_read_b128 v[196:199], v151 offset:34816
	ds_read_b128 v[200:203], v151 offset:35840
	ds_read_b128 v[204:207], v151 offset:36864
	ds_read_b128 v[208:211], v151 offset:37888
	ds_read_b128 v[212:215], v151 offset:38912
	ds_read_b128 v[216:219], v151 offset:39936
	global_load_lds_dwordx4 v128, s[42:43]
	s_mov_b32 m0, s61
	s_nop 0
	global_load_lds_dwordx4 v132, s[42:43]
	s_waitcnt vmcnt(8)
	s_waitcnt lgkmcnt(0)
	s_barrier
	v_mfma_f32_16x16x32_bf16 v[124:127], v[152:155], v[184:187], v[124:127]
	v_mfma_f32_16x16x32_bf16 v[120:123], v[160:163], v[184:187], v[120:123]
	v_mfma_f32_16x16x32_bf16 v[116:119], v[152:155], v[196:199], v[116:119]
	v_mfma_f32_16x16x32_bf16 v[108:111], v[160:163], v[196:199], v[108:111]
	v_mfma_f32_16x16x32_bf16 v[100:103], v[152:155], v[204:207], v[100:103]
	v_mfma_f32_16x16x32_bf16 v[92:95], v[160:163], v[204:207], v[92:95]
	v_mfma_f32_16x16x32_bf16 v[84:87], v[152:155], v[212:215], v[84:87]
	v_mfma_f32_16x16x32_bf16 v[76:79], v[160:163], v[212:215], v[76:79]
	v_mfma_f32_16x16x32_bf16 v[124:127], v[156:159], v[192:195], v[124:127]
	v_mfma_f32_16x16x32_bf16 v[120:123], v[164:167], v[192:195], v[120:123]
	v_mfma_f32_16x16x32_bf16 v[116:119], v[156:159], v[200:203], v[116:119]
	v_mfma_f32_16x16x32_bf16 v[108:111], v[164:167], v[200:203], v[108:111]
	v_mfma_f32_16x16x32_bf16 v[100:103], v[156:159], v[208:211], v[100:103]
	v_mfma_f32_16x16x32_bf16 v[92:95], v[164:167], v[208:211], v[92:95]
	v_mfma_f32_16x16x32_bf16 v[84:87], v[156:159], v[216:219], v[84:87]
	v_mfma_f32_16x16x32_bf16 v[76:79], v[164:167], v[216:219], v[76:79]
	v_mfma_f32_16x16x32_bf16 v[112:115], v[168:171], v[184:187], v[112:115]
	v_mfma_f32_16x16x32_bf16 v[104:107], v[176:179], v[184:187], v[104:107]
	v_mfma_f32_16x16x32_bf16 v[96:99], v[168:171], v[196:199], v[96:99]
	v_mfma_f32_16x16x32_bf16 v[88:91], v[176:179], v[196:199], v[88:91]
	v_mfma_f32_16x16x32_bf16 v[80:83], v[168:171], v[204:207], v[80:83]
	v_mfma_f32_16x16x32_bf16 v[72:75], v[176:179], v[204:207], v[72:75]
	v_mfma_f32_16x16x32_bf16 v[68:71], v[168:171], v[212:215], v[68:71]
	v_mfma_f32_16x16x32_bf16 v[64:67], v[176:179], v[212:215], v[64:67]
	v_mfma_f32_16x16x32_bf16 v[112:115], v[172:175], v[192:195], v[112:115]
	v_mfma_f32_16x16x32_bf16 v[104:107], v[180:183], v[192:195], v[104:107]
	v_mfma_f32_16x16x32_bf16 v[96:99], v[172:175], v[200:203], v[96:99]
	v_mfma_f32_16x16x32_bf16 v[88:91], v[180:183], v[200:203], v[88:91]
	v_mfma_f32_16x16x32_bf16 v[80:83], v[172:175], v[208:211], v[80:83]
	v_mfma_f32_16x16x32_bf16 v[72:75], v[180:183], v[208:211], v[72:75]
	v_mfma_f32_16x16x32_bf16 v[68:71], v[172:175], v[216:219], v[68:71]
	v_mfma_f32_16x16x32_bf16 v[64:67], v[180:183], v[216:219], v[64:67]
	s_barrier
	s_add_i32 s42, s76, s59
	s_mov_b32 m0, s42
	ds_read_b128 v[184:187], v151 offset:49152
	ds_read_b128 v[192:195], v151 offset:50176
	ds_read_b128 v[196:199], v151 offset:51200
	ds_read_b128 v[200:203], v151 offset:52224
	ds_read_b128 v[204:207], v151 offset:53248
	ds_read_b128 v[208:211], v151 offset:54272
	ds_read_b128 v[212:215], v151 offset:55296
	ds_read_b128 v[216:219], v151 offset:56320
	global_load_lds_dwordx4 v130, s[98:99]
	s_add_i32 m0, s42, 0x2000
	s_add_u32 s34, s34, 0x100080
	s_addc_u32 s35, s35, 0
	s_add_i32 s42, s77, s59
	global_load_lds_dwordx4 v134, s[98:99]
	s_mov_b32 m0, s42
	s_nop 0
	global_load_lds_dwordx4 v130, s[34:35]
	s_add_i32 m0, s42, 0x2000
	s_nop 0
	global_load_lds_dwordx4 v134, s[34:35]
	s_mov_b32 m0, s63
	s_nop 0
	global_load_lds_dwordx4 v128, s[100:101]
	s_mov_b32 m0, s64
	s_nop 0
	global_load_lds_dwordx4 v132, s[100:101]
	s_waitcnt vmcnt(8)
	s_waitcnt lgkmcnt(0)
	s_barrier
	v_mfma_f32_16x16x32_bf16 v[60:63], v[152:155], v[184:187], v[60:63]
	v_mfma_f32_16x16x32_bf16 v[56:59], v[160:163], v[184:187], v[56:59]
	v_mfma_f32_16x16x32_bf16 v[52:55], v[152:155], v[196:199], v[52:55]
	v_mfma_f32_16x16x32_bf16 v[44:47], v[160:163], v[196:199], v[44:47]
	v_mfma_f32_16x16x32_bf16 v[36:39], v[152:155], v[204:207], v[36:39]
	v_mfma_f32_16x16x32_bf16 v[28:31], v[160:163], v[204:207], v[28:31]
	v_mfma_f32_16x16x32_bf16 v[20:23], v[152:155], v[212:215], v[20:23]
	v_mfma_f32_16x16x32_bf16 v[12:15], v[160:163], v[212:215], v[12:15]
	v_mfma_f32_16x16x32_bf16 v[60:63], v[156:159], v[192:195], v[60:63]
	v_mfma_f32_16x16x32_bf16 v[56:59], v[164:167], v[192:195], v[56:59]
	v_mfma_f32_16x16x32_bf16 v[52:55], v[156:159], v[200:203], v[52:55]
	v_mfma_f32_16x16x32_bf16 v[44:47], v[164:167], v[200:203], v[44:47]
	v_mfma_f32_16x16x32_bf16 v[36:39], v[156:159], v[208:211], v[36:39]
	v_mfma_f32_16x16x32_bf16 v[28:31], v[164:167], v[208:211], v[28:31]
	v_mfma_f32_16x16x32_bf16 v[20:23], v[156:159], v[216:219], v[20:23]
	v_mfma_f32_16x16x32_bf16 v[12:15], v[164:167], v[216:219], v[12:15]
	v_mfma_f32_16x16x32_bf16 v[48:51], v[168:171], v[184:187], v[48:51]
	v_mfma_f32_16x16x32_bf16 v[40:43], v[176:179], v[184:187], v[40:43]
	v_mfma_f32_16x16x32_bf16 v[32:35], v[168:171], v[196:199], v[32:35]
	v_mfma_f32_16x16x32_bf16 v[24:27], v[176:179], v[196:199], v[24:27]
	v_mfma_f32_16x16x32_bf16 v[16:19], v[168:171], v[204:207], v[16:19]
	v_mfma_f32_16x16x32_bf16 v[8:11], v[176:179], v[204:207], v[8:11]
	v_mfma_f32_16x16x32_bf16 v[4:7], v[168:171], v[212:215], v[4:7]
	v_mfma_f32_16x16x32_bf16 v[0:3], v[176:179], v[212:215], v[0:3]
	v_mfma_f32_16x16x32_bf16 v[48:51], v[172:175], v[192:195], v[48:51]
	v_mfma_f32_16x16x32_bf16 v[40:43], v[180:183], v[192:195], v[40:43]
	v_mfma_f32_16x16x32_bf16 v[32:35], v[172:175], v[200:203], v[32:35]
	v_mfma_f32_16x16x32_bf16 v[24:27], v[180:183], v[200:203], v[24:27]
	v_mfma_f32_16x16x32_bf16 v[16:19], v[172:175], v[208:211], v[16:19]
	v_mfma_f32_16x16x32_bf16 v[8:11], v[180:183], v[208:211], v[8:11]
	v_mfma_f32_16x16x32_bf16 v[4:7], v[172:175], v[216:219], v[4:7]
	v_mfma_f32_16x16x32_bf16 v[0:3], v[180:183], v[216:219], v[0:3]
	s_barrier
	s_add_i32 s75, s75, 2
	s_add_u32 s30, s30, 0x100
	s_addc_u32 s31, s31, 0
	s_add_u32 s73, s73, 0x100
	s_addc_u32 s74, s74, 0
	s_cmp_gt_u32 s75, 61
	s_cbranch_scc0 .LBB0_1650
